# v13 + permlane16_swap also in the 3 remaining LN statistic blocks and the 15 G3 key-norm swizzles
# speedup vs baseline: 1.0043x; 1.0007x over previous
.LBB0_239:
	s_waitcnt lgkmcnt(0)
	v_readlane_b32 s2, v254, 27
	s_mul_i32 s2, s2, 0xb4000
	v_readlane_b32 s3, v254, 28
	s_add_u32 s2, s22, s2
	s_addc_u32 s3, s23, 0
	s_add_u32 s59, s2, 0x100000
	s_addc_u32 s67, s3, 0
	s_lshr_b32 s2, s72, 14
	s_add_i32 s18, s2, 8
	s_ashr_i32 s19, s53, 4
	s_and_b64 s[2:3], s[56:57], exec
	s_cselect_b32 s2, s18, s19
	s_mul_hi_i32 s3, s2, 0x4800
	s_mulk_i32 s2, 0x4800
	s_lshl_b32 s69, s82, 8
	s_lshl_b64 s[18:19], s[2:3], 2
	v_or_b32_e32 v132, s69, v177
	s_add_u32 s2, s59, s18
	s_addc_u32 s3, s67, s19
	v_ashrrev_i32_e32 v133, 31, v132
	v_lshl_add_u64 v[132:133], v[132:133], 2, s[2:3]
	s_mov_b64 s[2:3], 0x4000
	v_or_b32_e32 v148, v179, v178
	v_lshl_add_u64 v[144:145], v[132:133], 0, s[2:3]
	s_movk_i32 s2, 0x4000
	v_add_u32_e32 v148, s69, v148
	v_add_co_u32_e32 v140, vcc, s2, v132
	v_ashrrev_i32_e32 v149, 31, v148
	v_readlane_b32 s2, v254, 48
	v_lshl_add_u64 v[152:153], v[148:149], 2, s[14:15]
	v_readlane_b32 s3, v254, 49
	v_addc_co_u32_e32 v141, vcc, 0, v133, vcc
	v_lshl_add_u64 v[154:155], v[152:153], 0, s[28:29]
	v_lshl_add_u64 v[162:163], v[152:153], 0, s[2:3]
	v_readlane_b32 s2, v254, 52
	global_load_dwordx4 v[132:135], v[144:145], off offset:64
	global_load_dwordx4 v[136:139], v[144:145], off offset:512
	s_nop 0
	global_load_dwordx4 v[140:143], v[140:141], off
	s_nop 0
	global_load_dwordx4 v[144:147], v[144:145], off offset:576
	s_nop 0
	global_load_dwordx4 v[148:151], v[154:155], off nt
	s_nop 0
	global_load_dwordx4 v[154:157], v[154:155], off offset:512 nt
	s_nop 0
	global_load_dwordx4 v[158:161], v[162:163], off nt
	global_load_dwordx4 v[170:173], v[162:163], off offset:512 nt
	v_lshl_add_u64 v[162:163], v[152:153], 0, s[36:37]
	v_readlane_b32 s3, v254, 53
	global_load_dwordx4 v[186:189], v[162:163], off nt
	global_load_dwordx4 v[190:193], v[162:163], off offset:512 nt
	v_lshl_add_u64 v[162:163], v[152:153], 0, s[2:3]
	v_readlane_b32 s2, v254, 56
	global_load_dwordx4 v[194:197], v[162:163], off nt
	global_load_dwordx4 v[198:201], v[162:163], off offset:512 nt
	v_lshl_add_u64 v[162:163], v[152:153], 0, s[42:43]
	v_readlane_b32 s3, v254, 57
	global_load_dwordx4 v[202:205], v[162:163], off nt
	global_load_dwordx4 v[214:217], v[162:163], off offset:512 nt
	v_lshl_add_u64 v[162:163], v[152:153], 0, s[2:3]
	v_readlane_b32 s2, v254, 60
	global_load_dwordx4 v[218:221], v[162:163], off nt
	global_load_dwordx4 v[222:225], v[162:163], off offset:512 nt
	v_lshl_add_u64 v[162:163], v[152:153], 0, s[48:49]
	v_readlane_b32 s3, v254, 61
	global_load_dwordx4 v[226:229], v[162:163], off nt
	global_load_dwordx4 v[230:233], v[162:163], off offset:512 nt
	v_lshl_add_u64 v[162:163], v[152:153], 0, s[2:3]
	global_load_dwordx4 v[234:237], v[162:163], off nt
	global_load_dwordx4 v[238:241], v[162:163], off offset:512 nt
	s_waitcnt vmcnt(0)
	ds_write_b128 v176, v[148:151]
	ds_write_b128 v176, v[158:161] offset:1152
	ds_read_b128 v[148:151], v175
	ds_read_b128 v[158:161], v175 offset:64
	ds_write_b128 v176, v[154:157]
	ds_write_b128 v176, v[170:173] offset:1152
	ds_read_b128 v[154:157], v175
	ds_read_b128 v[170:173], v175 offset:64
	v_pk_add_f32 v[142:143], v[142:143], 1.0 op_sel_hi:[1,0]
	v_pk_add_f32 v[162:163], v[140:141], 1.0 op_sel_hi:[1,0]
	ds_write_b128 v176, v[186:189]
	ds_write_b128 v176, v[194:197] offset:1152
	v_pk_mul_f32 v[140:141], v[142:143], 0.5 op_sel_hi:[1,0]
	v_pk_mul_f32 v[142:143], v[162:163], 0.5 op_sel_hi:[1,0]
	s_waitcnt lgkmcnt(6)
	v_pk_mul_f32 v[162:163], v[160:161], s[80:81] op_sel_hi:[1,0]
	v_pk_mul_f32 v[206:207], v[158:159], s[80:81] op_sel_hi:[1,0]
	ds_read_b128 v[158:161], v175
	ds_read_b128 v[186:189], v175 offset:64
	v_pk_mul_f32 v[150:151], v[150:151], s[80:81] op_sel_hi:[1,0]
	v_pk_mul_f32 v[148:149], v[148:149], s[80:81] op_sel_hi:[1,0]
	v_pk_add_f32 v[134:135], v[134:135], 1.0 op_sel_hi:[1,0]
	v_pk_add_f32 v[132:133], v[132:133], 1.0 op_sel_hi:[1,0]
	v_pk_fma_f32 v[130:131], v[130:131], v[140:141], v[150:151]
	v_pk_fma_f32 v[128:129], v[128:129], v[142:143], v[148:149]
	v_pk_mul_f32 v[148:149], v[134:135], 0.5 op_sel_hi:[1,0]
	v_pk_mul_f32 v[150:151], v[132:133], 0.5 op_sel_hi:[1,0]
	v_pk_fma_f32 v[134:135], v[126:127], v[148:149], v[162:163]
	v_pk_fma_f32 v[132:133], v[124:125], v[150:151], v[206:207]
	v_pk_add_f32 v[124:125], v[138:139], 1.0 op_sel_hi:[1,0]
	v_pk_add_f32 v[126:127], v[136:137], 1.0 op_sel_hi:[1,0]
	s_waitcnt lgkmcnt(5)
	v_pk_mul_f32 v[156:157], v[156:157], s[80:81] op_sel_hi:[1,0]
	v_pk_mul_f32 v[154:155], v[154:155], s[80:81] op_sel_hi:[1,0]
	v_pk_mul_f32 v[124:125], v[124:125], 0.5 op_sel_hi:[1,0]
	v_pk_mul_f32 v[126:127], v[126:127], 0.5 op_sel_hi:[1,0]
	ds_write_b128 v176, v[190:193]
	ds_write_b128 v176, v[198:201] offset:1152
	v_pk_fma_f32 v[138:139], v[122:123], v[124:125], v[156:157]
	v_pk_fma_f32 v[136:137], v[120:121], v[126:127], v[154:155]
	s_waitcnt lgkmcnt(6)
	v_pk_mul_f32 v[162:163], v[172:173], s[80:81] op_sel_hi:[1,0]
	v_pk_mul_f32 v[194:195], v[170:171], s[80:81] op_sel_hi:[1,0]
	ds_read_b128 v[154:157], v175
	ds_read_b128 v[170:173], v175 offset:64
	v_pk_add_f32 v[120:121], v[146:147], 1.0 op_sel_hi:[1,0]
	v_pk_add_f32 v[122:123], v[144:145], 1.0 op_sel_hi:[1,0]
	v_pk_mul_f32 v[120:121], v[120:121], 0.5 op_sel_hi:[1,0]
	v_pk_mul_f32 v[122:123], v[122:123], 0.5 op_sel_hi:[1,0]
	v_pk_fma_f32 v[146:147], v[106:107], v[120:121], v[162:163]
	v_pk_fma_f32 v[144:145], v[104:105], v[122:123], v[194:195]
	s_waitcnt lgkmcnt(5)
	v_pk_mul_f32 v[104:105], v[160:161], s[80:81] op_sel_hi:[1,0]
	v_pk_mul_f32 v[106:107], v[158:159], s[80:81] op_sel_hi:[1,0]
	v_pk_fma_f32 v[110:111], v[110:111], v[140:141], v[104:105]
	v_pk_fma_f32 v[108:109], v[108:109], v[142:143], v[106:107]
	s_waitcnt lgkmcnt(4)
	v_pk_mul_f32 v[104:105], v[188:189], s[80:81] op_sel_hi:[1,0]
	v_pk_mul_f32 v[106:107], v[186:187], s[80:81] op_sel_hi:[1,0]
	v_pk_fma_f32 v[118:119], v[118:119], v[148:149], v[104:105]
	v_pk_fma_f32 v[116:117], v[116:117], v[150:151], v[106:107]
	s_waitcnt lgkmcnt(1)
	v_pk_mul_f32 v[104:105], v[156:157], s[80:81] op_sel_hi:[1,0]
	v_pk_mul_f32 v[106:107], v[154:155], s[80:81] op_sel_hi:[1,0]
	v_pk_fma_f32 v[102:103], v[102:103], v[124:125], v[104:105]
	s_waitcnt lgkmcnt(0)
	v_pk_mul_f32 v[104:105], v[172:173], s[80:81] op_sel_hi:[1,0]
	v_pk_mul_f32 v[154:155], v[170:171], s[80:81] op_sel_hi:[1,0]
	v_pk_fma_f32 v[100:101], v[100:101], v[126:127], v[106:107]
	v_pk_fma_f32 v[106:107], v[98:99], v[120:121], v[104:105]
	v_pk_fma_f32 v[104:105], v[96:97], v[122:123], v[154:155]
	v_readlane_b32 s2, v255, 0
	v_lshl_add_u64 v[96:97], v[152:153], 0, s[54:55]
	v_readlane_b32 s3, v255, 1
	global_load_dwordx4 v[154:157], v[96:97], off nt
	global_load_dwordx4 v[158:161], v[96:97], off offset:512 nt
	v_lshl_add_u64 v[96:97], v[152:153], 0, s[2:3]
	v_readlane_b32 s2, v255, 2
	global_load_dwordx4 v[170:173], v[96:97], off nt
	global_load_dwordx4 v[186:189], v[96:97], off offset:512 nt
	v_lshl_add_u64 v[96:97], v[152:153], 0, s[60:61]
	v_readlane_b32 s3, v255, 3
	global_load_dwordx4 v[190:193], v[96:97], off nt
	global_load_dwordx4 v[194:197], v[96:97], off offset:512 nt
	v_lshl_add_u64 v[96:97], v[152:153], 0, s[2:3]
	global_load_dwordx4 v[198:201], v[96:97], off nt
	global_load_dwordx4 v[250:253], v[96:97], off offset:512 nt
	ds_write_b128 v176, v[202:205]
	ds_write_b128 v176, v[218:221] offset:1152
	ds_read_b128 v[96:99], v175
	ds_read_b128 v[202:205], v175 offset:64
	ds_write_b128 v176, v[214:217]
	ds_write_b128 v176, v[222:225] offset:1152
	ds_read_b128 v[214:217], v175
	ds_read_b128 v[218:221], v175 offset:64
	ds_write_b128 v176, v[226:229]
	ds_write_b128 v176, v[234:237] offset:1152
	ds_read_b128 v[222:225], v175
	ds_read_b128 v[226:229], v175 offset:64
	s_waitcnt lgkmcnt(9)
	v_pk_mul_f32 v[96:97], v[96:97], s[80:81] op_sel_hi:[1,0]
	v_pk_mul_f32 v[98:99], v[98:99], s[80:81] op_sel_hi:[1,0]
	v_pk_fma_f32 v[92:93], v[92:93], v[142:143], v[96:97]
	s_waitcnt lgkmcnt(8)
	v_pk_mul_f32 v[96:97], v[204:205], s[80:81] op_sel_hi:[1,0]
	v_pk_mul_f32 v[162:163], v[202:203], s[80:81] op_sel_hi:[1,0]
	v_pk_fma_f32 v[94:95], v[94:95], v[140:141], v[98:99]
	v_pk_fma_f32 v[98:99], v[90:91], v[148:149], v[96:97]
	v_pk_fma_f32 v[96:97], v[88:89], v[150:151], v[162:163]
	ds_write_b128 v176, v[230:233]
	ds_write_b128 v176, v[238:241] offset:1152
	s_waitcnt lgkmcnt(7)
	v_pk_mul_f32 v[88:89], v[216:217], s[80:81] op_sel_hi:[1,0]
	v_pk_mul_f32 v[90:91], v[214:215], s[80:81] op_sel_hi:[1,0]
	ds_read_b128 v[202:205], v175
	ds_read_b128 v[214:217], v175 offset:64
	v_pk_fma_f32 v[86:87], v[86:87], v[124:125], v[88:89]
	s_waitcnt lgkmcnt(8)
	v_pk_mul_f32 v[88:89], v[220:221], s[80:81] op_sel_hi:[1,0]
	v_pk_mul_f32 v[162:163], v[218:219], s[80:81] op_sel_hi:[1,0]
	v_pk_fma_f32 v[84:85], v[84:85], v[126:127], v[90:91]
	v_pk_fma_f32 v[90:91], v[74:75], v[120:121], v[88:89]
	v_pk_fma_f32 v[88:89], v[72:73], v[122:123], v[162:163]
	s_waitcnt lgkmcnt(5)
	v_pk_mul_f32 v[72:73], v[224:225], s[80:81] op_sel_hi:[1,0]
	v_pk_mul_f32 v[74:75], v[222:223], s[80:81] op_sel_hi:[1,0]
	v_pk_fma_f32 v[78:79], v[78:79], v[140:141], v[72:73]
	v_pk_fma_f32 v[76:77], v[76:77], v[142:143], v[74:75]
	s_waitcnt lgkmcnt(4)
	v_pk_mul_f32 v[72:73], v[228:229], s[80:81] op_sel_hi:[1,0]
	v_pk_mul_f32 v[74:75], v[226:227], s[80:81] op_sel_hi:[1,0]
	v_pk_fma_f32 v[82:83], v[82:83], v[148:149], v[72:73]
	v_pk_fma_f32 v[80:81], v[80:81], v[150:151], v[74:75]
	s_waitcnt lgkmcnt(1)
	v_pk_mul_f32 v[72:73], v[204:205], s[80:81] op_sel_hi:[1,0]
	v_pk_mul_f32 v[74:75], v[202:203], s[80:81] op_sel_hi:[1,0]
	v_pk_fma_f32 v[70:71], v[70:71], v[124:125], v[72:73]
	s_waitcnt lgkmcnt(0)
	v_pk_mul_f32 v[72:73], v[216:217], s[80:81] op_sel_hi:[1,0]
	v_pk_mul_f32 v[162:163], v[214:215], s[80:81] op_sel_hi:[1,0]
	v_pk_fma_f32 v[68:69], v[68:69], v[126:127], v[74:75]
	v_pk_fma_f32 v[74:75], v[66:67], v[120:121], v[72:73]
	v_pk_fma_f32 v[72:73], v[64:65], v[122:123], v[162:163]
	v_readlane_b32 s2, v255, 4
	v_lshl_add_u64 v[64:65], v[152:153], 0, s[70:71]
	v_readlane_b32 s3, v255, 5
	global_load_dwordx4 v[202:205], v[64:65], off nt
	global_load_dwordx4 v[214:217], v[64:65], off offset:512 nt
	v_lshl_add_u64 v[64:65], v[152:153], 0, s[2:3]
	v_readlane_b32 s2, v255, 6
	global_load_dwordx4 v[218:221], v[64:65], off nt
	global_load_dwordx4 v[222:225], v[64:65], off offset:512 nt
	v_lshl_add_u64 v[64:65], v[152:153], 0, s[96:97]
	v_readlane_b32 s3, v255, 7
	global_load_dwordx4 v[226:229], v[64:65], off nt
	global_load_dwordx4 v[230:233], v[64:65], off offset:512 nt
	v_lshl_add_u64 v[64:65], v[152:153], 0, s[2:3]
	global_load_dwordx4 v[234:237], v[64:65], off nt
	global_load_dwordx4 v[238:241], v[64:65], off offset:512 nt
	s_waitcnt vmcnt(15)
	ds_write_b128 v176, v[154:157]
	s_waitcnt vmcnt(13)
	ds_write_b128 v176, v[170:173] offset:1152
	ds_read_b128 v[64:67], v175
	ds_read_b128 v[152:155], v175 offset:64
	ds_write_b128 v176, v[158:161]
	s_waitcnt vmcnt(12)
	ds_write_b128 v176, v[186:189] offset:1152
	ds_read_b128 v[156:159], v175
	ds_read_b128 v[160:163], v175 offset:64
	s_waitcnt vmcnt(11)
	ds_write_b128 v176, v[190:193]
	s_waitcnt vmcnt(9)
	ds_write_b128 v176, v[198:201] offset:1152
	ds_read_b128 v[170:173], v175
	ds_read_b128 v[186:189], v175 offset:64
	s_waitcnt lgkmcnt(9)
	v_pk_mul_f32 v[64:65], v[64:65], s[80:81] op_sel_hi:[1,0]
	v_pk_mul_f32 v[66:67], v[66:67], s[80:81] op_sel_hi:[1,0]
	v_pk_fma_f32 v[60:61], v[60:61], v[142:143], v[64:65]
	s_waitcnt lgkmcnt(8)
	v_pk_mul_f32 v[64:65], v[154:155], s[80:81] op_sel_hi:[1,0]
	v_pk_mul_f32 v[152:153], v[152:153], s[80:81] op_sel_hi:[1,0]
	v_pk_fma_f32 v[62:63], v[62:63], v[140:141], v[66:67]
	v_pk_fma_f32 v[66:67], v[58:59], v[148:149], v[64:65]
	v_pk_fma_f32 v[64:65], v[56:57], v[150:151], v[152:153]
	ds_write_b128 v176, v[194:197]
	s_waitcnt vmcnt(8)
	ds_write_b128 v176, v[250:253] offset:1152
	s_waitcnt lgkmcnt(7)
	v_pk_mul_f32 v[56:57], v[158:159], s[80:81] op_sel_hi:[1,0]
	v_pk_mul_f32 v[58:59], v[156:157], s[80:81] op_sel_hi:[1,0]
	ds_read_b128 v[152:155], v175
	ds_read_b128 v[156:159], v175 offset:64
	v_pk_fma_f32 v[54:55], v[54:55], v[124:125], v[56:57]
	s_waitcnt lgkmcnt(8)
	v_pk_mul_f32 v[56:57], v[162:163], s[80:81] op_sel_hi:[1,0]
	v_pk_mul_f32 v[160:161], v[160:161], s[80:81] op_sel_hi:[1,0]
	v_pk_fma_f32 v[52:53], v[52:53], v[126:127], v[58:59]
	v_pk_fma_f32 v[58:59], v[42:43], v[120:121], v[56:57]
	v_pk_fma_f32 v[56:57], v[40:41], v[122:123], v[160:161]
	s_waitcnt lgkmcnt(5)
	v_pk_mul_f32 v[40:41], v[172:173], s[80:81] op_sel_hi:[1,0]
	v_pk_mul_f32 v[42:43], v[170:171], s[80:81] op_sel_hi:[1,0]
	v_pk_fma_f32 v[46:47], v[46:47], v[140:141], v[40:41]
	v_pk_fma_f32 v[44:45], v[44:45], v[142:143], v[42:43]
	s_waitcnt lgkmcnt(4)
	v_pk_mul_f32 v[40:41], v[188:189], s[80:81] op_sel_hi:[1,0]
	v_pk_mul_f32 v[42:43], v[186:187], s[80:81] op_sel_hi:[1,0]
	v_pk_fma_f32 v[50:51], v[50:51], v[148:149], v[40:41]
	v_pk_fma_f32 v[48:49], v[48:49], v[150:151], v[42:43]
	s_waitcnt lgkmcnt(1)
	v_pk_mul_f32 v[40:41], v[154:155], s[80:81] op_sel_hi:[1,0]
	v_pk_mul_f32 v[42:43], v[152:153], s[80:81] op_sel_hi:[1,0]
	v_pk_fma_f32 v[38:39], v[38:39], v[124:125], v[40:41]
	s_waitcnt lgkmcnt(0)
	v_pk_mul_f32 v[40:41], v[158:159], s[80:81] op_sel_hi:[1,0]
	v_pk_mul_f32 v[152:153], v[156:157], s[80:81] op_sel_hi:[1,0]
	v_pk_fma_f32 v[36:37], v[36:37], v[126:127], v[42:43]
	v_pk_fma_f32 v[42:43], v[34:35], v[120:121], v[40:41]
	v_pk_fma_f32 v[40:41], v[32:33], v[122:123], v[152:153]
	s_nop 0
	s_waitcnt vmcnt(7)
	ds_write_b128 v176, v[202:205]
	s_waitcnt vmcnt(5)
	ds_write_b128 v176, v[218:221] offset:1152
	ds_read_b128 v[32:35], v175
	ds_read_b128 v[152:155], v175 offset:64
	ds_write_b128 v176, v[214:217]
	s_waitcnt vmcnt(4)
	ds_write_b128 v176, v[222:225] offset:1152
	ds_read_b128 v[156:159], v175
	ds_read_b128 v[160:163], v175 offset:64
	s_waitcnt vmcnt(3)
	ds_write_b128 v176, v[226:229]
	s_waitcnt vmcnt(1)
	ds_write_b128 v176, v[234:237] offset:1152
	ds_read_b128 v[170:173], v175
	ds_read_b128 v[186:189], v175 offset:64
	s_waitcnt lgkmcnt(9)
	v_pk_mul_f32 v[32:33], v[32:33], s[80:81] op_sel_hi:[1,0]
	v_pk_mul_f32 v[34:35], v[34:35], s[80:81] op_sel_hi:[1,0]
	v_pk_fma_f32 v[28:29], v[28:29], v[142:143], v[32:33]
	s_waitcnt lgkmcnt(8)
	v_pk_mul_f32 v[32:33], v[154:155], s[80:81] op_sel_hi:[1,0]
	v_pk_mul_f32 v[152:153], v[152:153], s[80:81] op_sel_hi:[1,0]
	v_pk_fma_f32 v[30:31], v[30:31], v[140:141], v[34:35]
	v_pk_fma_f32 v[34:35], v[26:27], v[148:149], v[32:33]
	v_pk_fma_f32 v[32:33], v[24:25], v[150:151], v[152:153]
	ds_write_b128 v176, v[230:233]
	s_waitcnt vmcnt(0)
	ds_write_b128 v176, v[238:241] offset:1152
	s_waitcnt lgkmcnt(7)
	v_pk_mul_f32 v[24:25], v[158:159], s[80:81] op_sel_hi:[1,0]
	v_pk_mul_f32 v[26:27], v[156:157], s[80:81] op_sel_hi:[1,0]
	ds_read_b128 v[152:155], v175
	ds_read_b128 v[156:159], v175 offset:64
	v_pk_fma_f32 v[22:23], v[22:23], v[124:125], v[24:25]
	s_waitcnt lgkmcnt(8)
	v_pk_mul_f32 v[24:25], v[162:163], s[80:81] op_sel_hi:[1,0]
	v_pk_mul_f32 v[160:161], v[160:161], s[80:81] op_sel_hi:[1,0]
	v_pk_fma_f32 v[20:21], v[20:21], v[126:127], v[26:27]
	v_pk_fma_f32 v[26:27], v[14:15], v[120:121], v[24:25]
	v_pk_fma_f32 v[24:25], v[12:13], v[122:123], v[160:161]
	s_waitcnt lgkmcnt(5)
	v_pk_mul_f32 v[12:13], v[172:173], s[80:81] op_sel_hi:[1,0]
	v_pk_mul_f32 v[160:161], v[170:171], s[80:81] op_sel_hi:[1,0]
	v_pk_fma_f32 v[14:15], v[114:115], v[140:141], v[12:13]
	v_pk_fma_f32 v[12:13], v[112:113], v[142:143], v[160:161]
	s_waitcnt lgkmcnt(4)
	v_pk_mul_f32 v[112:113], v[188:189], s[80:81] op_sel_hi:[1,0]
	v_pk_mul_f32 v[114:115], v[186:187], s[80:81] op_sel_hi:[1,0]
	v_pk_fma_f32 v[18:19], v[18:19], v[148:149], v[112:113]
	v_pk_fma_f32 v[16:17], v[16:17], v[150:151], v[114:115]
	s_waitcnt lgkmcnt(1)
	v_pk_mul_f32 v[112:113], v[154:155], s[80:81] op_sel_hi:[1,0]
	v_pk_mul_f32 v[114:115], v[152:153], s[80:81] op_sel_hi:[1,0]
	v_pk_fma_f32 v[6:7], v[6:7], v[124:125], v[112:113]
	s_waitcnt lgkmcnt(0)
	v_pk_mul_f32 v[112:113], v[158:159], s[80:81] op_sel_hi:[1,0]
	v_pk_fma_f32 v[4:5], v[4:5], v[126:127], v[114:115]
	v_pk_mul_f32 v[114:115], v[156:157], s[80:81] op_sel_hi:[1,0]
	v_pk_fma_f32 v[10:11], v[10:11], v[120:121], v[112:113]
	v_add_f32_e32 v112, v128, v129
	v_add_f32_e32 v113, v130, v131
	v_pk_fma_f32 v[8:9], v[8:9], v[122:123], v[114:115]
	v_add_f32_e32 v112, v112, v113
	v_mul_f32_e32 v113, v129, v129
	v_mul_f32_e32 v114, v131, v131
	v_fmac_f32_e32 v113, v128, v128
	v_fmac_f32_e32 v114, v130, v130
	v_add_f32_e32 v113, v113, v114
	v_add_f32_e32 v114, v132, v133
	v_add_f32_e32 v115, v134, v135
	v_add_f32_e32 v112, 0, v112
	v_add_f32_e32 v114, v114, v115
	v_add_f32_e32 v112, v114, v112
	v_mul_f32_e32 v114, v133, v133
	v_mul_f32_e32 v115, v135, v135
	v_fmac_f32_e32 v114, v132, v132
	v_fmac_f32_e32 v115, v134, v134
	v_add_f32_e32 v114, v114, v115
	v_add_f32_e32 v113, v113, v114
	v_add_f32_e32 v114, v136, v137
	v_add_f32_e32 v115, v138, v139
	v_add_f32_e32 v114, v114, v115
	v_add_f32_e32 v112, v114, v112
	v_mul_f32_e32 v114, v137, v137
	v_mul_f32_e32 v115, v139, v139
	v_fmac_f32_e32 v114, v136, v136
	v_fmac_f32_e32 v115, v138, v138
	v_add_f32_e32 v114, v114, v115
	v_add_f32_e32 v113, v114, v113
	v_add_f32_e32 v114, v144, v145
	v_add_f32_e32 v115, v146, v147
	v_add_f32_e32 v114, v114, v115
	v_add_f32_e32 v112, v114, v112
	v_mul_f32_e32 v114, v145, v145
	v_mul_f32_e32 v115, v147, v147
	v_fmac_f32_e32 v114, v144, v144
	v_fmac_f32_e32 v115, v146, v146
	v_add_f32_e32 v114, v114, v115
	v_add_f32_e32 v113, v114, v113
	v_mov_b32_e32 v114, v112
	v_mov_b32_e32 v115, v113
	s_nop 0
	v_permlane16_swap_b32_e32 v112, v114
	v_permlane16_swap_b32_e32 v113, v115
	v_add_f32_e32 v112, v112, v114
	v_add_f32_e32 v113, v113, v115
	v_mov_b32_e32 v114, v112
	v_mov_b32_e32 v115, v113
	s_nop 0
	v_permlane32_swap_b32_e32 v112, v114
	v_permlane32_swap_b32_e32 v113, v115
	s_and_saveexec_b64 s[2:3], s[8:9]
	v_pk_add_f32 v[112:113], v[112:113], v[114:115]
	ds_write_b64 v184, v[112:113]
	s_or_b64 exec, exec, s[2:3]
	v_add_f32_e32 v112, v108, v109
	v_add_f32_e32 v113, v110, v111
	v_add_f32_e32 v112, v112, v113
	v_mul_f32_e32 v113, v109, v109
	v_mul_f32_e32 v114, v111, v111
	v_fmac_f32_e32 v113, v108, v108
	v_fmac_f32_e32 v114, v110, v110
	v_add_f32_e32 v113, v113, v114
	v_add_f32_e32 v114, v116, v117
	v_add_f32_e32 v115, v118, v119
	v_add_f32_e32 v112, 0, v112
	v_add_f32_e32 v114, v114, v115
	v_add_f32_e32 v112, v114, v112
	v_mul_f32_e32 v114, v117, v117
	v_mul_f32_e32 v115, v119, v119
	v_fmac_f32_e32 v114, v116, v116
	v_fmac_f32_e32 v115, v118, v118
	v_add_f32_e32 v114, v114, v115
	v_add_f32_e32 v113, v113, v114
	v_add_f32_e32 v114, v100, v101
	v_add_f32_e32 v115, v102, v103
	v_add_f32_e32 v114, v114, v115
	v_add_f32_e32 v112, v114, v112
	v_mul_f32_e32 v114, v101, v101
	v_mul_f32_e32 v115, v103, v103
	v_fmac_f32_e32 v114, v100, v100
	v_fmac_f32_e32 v115, v102, v102
	v_add_f32_e32 v114, v114, v115
	v_add_f32_e32 v113, v114, v113
	v_add_f32_e32 v114, v104, v105
	v_add_f32_e32 v115, v106, v107
	v_add_f32_e32 v114, v114, v115
	v_add_f32_e32 v112, v114, v112
	v_mul_f32_e32 v114, v105, v105
	v_mul_f32_e32 v115, v107, v107
	v_fmac_f32_e32 v114, v104, v104
	v_fmac_f32_e32 v115, v106, v106
	v_add_f32_e32 v114, v114, v115
	v_add_f32_e32 v113, v114, v113
	v_mov_b32_e32 v114, v112
	v_mov_b32_e32 v115, v113
	s_nop 0
	v_permlane16_swap_b32_e32 v112, v114
	v_permlane16_swap_b32_e32 v113, v115
	v_add_f32_e32 v112, v112, v114
	v_add_f32_e32 v113, v113, v115
	v_mov_b32_e32 v114, v112
	v_mov_b32_e32 v115, v113
	s_nop 0
	v_permlane32_swap_b32_e32 v112, v114
	v_permlane32_swap_b32_e32 v113, v115
	s_and_saveexec_b64 s[2:3], s[8:9]
	v_pk_add_f32 v[112:113], v[112:113], v[114:115]
	ds_write_b64 v184, v[112:113] offset:512
	s_or_b64 exec, exec, s[2:3]
	v_add_f32_e32 v112, v92, v93
	v_add_f32_e32 v113, v94, v95
	v_add_f32_e32 v112, v112, v113
	v_mul_f32_e32 v113, v93, v93
	v_mul_f32_e32 v114, v95, v95
	v_fmac_f32_e32 v113, v92, v92
	v_fmac_f32_e32 v114, v94, v94
	v_add_f32_e32 v113, v113, v114
	v_add_f32_e32 v114, v96, v97
	v_add_f32_e32 v115, v98, v99
	v_add_f32_e32 v112, 0, v112
	v_add_f32_e32 v114, v114, v115
	v_add_f32_e32 v112, v114, v112
	v_mul_f32_e32 v114, v97, v97
	v_mul_f32_e32 v115, v99, v99
	v_fmac_f32_e32 v114, v96, v96
	v_fmac_f32_e32 v115, v98, v98
	v_add_f32_e32 v114, v114, v115
	v_add_f32_e32 v113, v113, v114
	v_add_f32_e32 v114, v84, v85
	v_add_f32_e32 v115, v86, v87
	v_add_f32_e32 v114, v114, v115
	v_add_f32_e32 v112, v114, v112
	v_mul_f32_e32 v114, v85, v85
	v_mul_f32_e32 v115, v87, v87
	v_fmac_f32_e32 v114, v84, v84
	v_fmac_f32_e32 v115, v86, v86
	v_add_f32_e32 v114, v114, v115
	v_add_f32_e32 v113, v114, v113
	v_add_f32_e32 v114, v88, v89
	v_add_f32_e32 v115, v90, v91
	v_add_f32_e32 v114, v114, v115
	v_add_f32_e32 v112, v114, v112
	v_mul_f32_e32 v114, v89, v89
	v_mul_f32_e32 v115, v91, v91
	v_fmac_f32_e32 v114, v88, v88
	v_fmac_f32_e32 v115, v90, v90
	v_add_f32_e32 v114, v114, v115
	v_add_f32_e32 v113, v114, v113
	v_mov_b32_e32 v114, v112
	v_mov_b32_e32 v115, v113
	s_nop 0
	v_permlane16_swap_b32_e32 v112, v114
	v_permlane16_swap_b32_e32 v113, v115
	v_add_f32_e32 v112, v112, v114
	v_add_f32_e32 v113, v113, v115
	v_mov_b32_e32 v114, v112
	v_mov_b32_e32 v115, v113
	s_nop 0
	v_permlane32_swap_b32_e32 v112, v114
	v_permlane32_swap_b32_e32 v113, v115
	s_and_saveexec_b64 s[2:3], s[8:9]
	v_pk_add_f32 v[112:113], v[112:113], v[114:115]
	ds_write_b64 v184, v[112:113] offset:1024
	s_or_b64 exec, exec, s[2:3]
	v_add_f32_e32 v112, v76, v77
	v_add_f32_e32 v113, v78, v79
	v_add_f32_e32 v112, v112, v113
	v_mul_f32_e32 v113, v77, v77
	v_mul_f32_e32 v114, v79, v79
	v_fmac_f32_e32 v113, v76, v76
	v_fmac_f32_e32 v114, v78, v78
	v_add_f32_e32 v113, v113, v114
	v_add_f32_e32 v114, v80, v81
	v_add_f32_e32 v115, v82, v83
	v_add_f32_e32 v112, 0, v112
	v_add_f32_e32 v114, v114, v115
	v_add_f32_e32 v112, v114, v112
	v_mul_f32_e32 v114, v81, v81
	v_mul_f32_e32 v115, v83, v83
	v_fmac_f32_e32 v114, v80, v80
	v_fmac_f32_e32 v115, v82, v82
	v_add_f32_e32 v114, v114, v115
	v_add_f32_e32 v113, v113, v114
	v_add_f32_e32 v114, v68, v69
	v_add_f32_e32 v115, v70, v71
	v_add_f32_e32 v114, v114, v115
	v_add_f32_e32 v112, v114, v112
	v_mul_f32_e32 v114, v69, v69
	v_mul_f32_e32 v115, v71, v71
	v_fmac_f32_e32 v114, v68, v68
	v_fmac_f32_e32 v115, v70, v70
	v_add_f32_e32 v114, v114, v115
	v_add_f32_e32 v113, v114, v113
	v_add_f32_e32 v114, v72, v73
	v_add_f32_e32 v115, v74, v75
	v_add_f32_e32 v114, v114, v115
	v_add_f32_e32 v112, v114, v112
	v_mul_f32_e32 v114, v73, v73
	v_mul_f32_e32 v115, v75, v75
	v_fmac_f32_e32 v114, v72, v72
	v_fmac_f32_e32 v115, v74, v74
	v_add_f32_e32 v114, v114, v115
	v_add_f32_e32 v113, v114, v113
	v_mov_b32_e32 v114, v112
	v_mov_b32_e32 v115, v113
	s_nop 0
	v_permlane16_swap_b32_e32 v112, v114
	v_permlane16_swap_b32_e32 v113, v115
	v_add_f32_e32 v112, v112, v114
	v_add_f32_e32 v113, v113, v115
	v_mov_b32_e32 v114, v112
	v_mov_b32_e32 v115, v113
	s_nop 0
	v_permlane32_swap_b32_e32 v112, v114
	v_permlane32_swap_b32_e32 v113, v115
	s_and_saveexec_b64 s[2:3], s[8:9]
	v_pk_add_f32 v[112:113], v[112:113], v[114:115]
	ds_write_b64 v184, v[112:113] offset:1536
	s_or_b64 exec, exec, s[2:3]
	v_add_f32_e32 v112, v60, v61
	v_add_f32_e32 v113, v62, v63
	v_add_f32_e32 v112, v112, v113
	v_mul_f32_e32 v113, v61, v61
	v_mul_f32_e32 v114, v63, v63
	v_fmac_f32_e32 v113, v60, v60
	v_fmac_f32_e32 v114, v62, v62
	v_add_f32_e32 v113, v113, v114
	v_add_f32_e32 v114, v64, v65
	v_add_f32_e32 v115, v66, v67
	v_add_f32_e32 v112, 0, v112
	v_add_f32_e32 v114, v114, v115
	v_add_f32_e32 v112, v114, v112
	v_mul_f32_e32 v114, v65, v65
	v_mul_f32_e32 v115, v67, v67
	v_fmac_f32_e32 v114, v64, v64
	v_fmac_f32_e32 v115, v66, v66
	v_add_f32_e32 v114, v114, v115
	v_add_f32_e32 v113, v113, v114
	v_add_f32_e32 v114, v52, v53
	v_add_f32_e32 v115, v54, v55
	v_add_f32_e32 v114, v114, v115
	v_add_f32_e32 v112, v114, v112
	v_mul_f32_e32 v114, v53, v53
	v_mul_f32_e32 v115, v55, v55
	v_fmac_f32_e32 v114, v52, v52
	v_fmac_f32_e32 v115, v54, v54
	v_add_f32_e32 v114, v114, v115
	v_add_f32_e32 v113, v114, v113
	v_add_f32_e32 v114, v56, v57
	v_add_f32_e32 v115, v58, v59
	v_add_f32_e32 v114, v114, v115
	v_add_f32_e32 v112, v114, v112
	v_mul_f32_e32 v114, v57, v57
	v_mul_f32_e32 v115, v59, v59
	v_fmac_f32_e32 v114, v56, v56
	v_fmac_f32_e32 v115, v58, v58
	v_add_f32_e32 v114, v114, v115
	v_add_f32_e32 v113, v114, v113
	v_mov_b32_e32 v114, v112
	v_mov_b32_e32 v115, v113
	s_nop 0
	v_permlane16_swap_b32_e32 v112, v114
	v_permlane16_swap_b32_e32 v113, v115
	v_add_f32_e32 v112, v112, v114
	v_add_f32_e32 v113, v113, v115
	v_mov_b32_e32 v114, v112
	v_mov_b32_e32 v115, v113
	s_nop 0
	v_permlane32_swap_b32_e32 v112, v114
	v_permlane32_swap_b32_e32 v113, v115
	s_and_saveexec_b64 s[2:3], s[8:9]
	v_pk_add_f32 v[112:113], v[112:113], v[114:115]
	ds_write_b64 v184, v[112:113] offset:4096
	s_or_b64 exec, exec, s[2:3]
	v_add_f32_e32 v112, v44, v45
	v_add_f32_e32 v113, v46, v47
	v_add_f32_e32 v112, v112, v113
	v_mul_f32_e32 v113, v45, v45
	v_mul_f32_e32 v114, v47, v47
	v_fmac_f32_e32 v113, v44, v44
	v_fmac_f32_e32 v114, v46, v46
	v_add_f32_e32 v113, v113, v114
	v_add_f32_e32 v114, v48, v49
	v_add_f32_e32 v115, v50, v51
	v_add_f32_e32 v112, 0, v112
	v_add_f32_e32 v114, v114, v115
	v_add_f32_e32 v112, v114, v112
	v_mul_f32_e32 v114, v49, v49
	v_mul_f32_e32 v115, v51, v51
	v_fmac_f32_e32 v114, v48, v48
	v_fmac_f32_e32 v115, v50, v50
	v_add_f32_e32 v114, v114, v115
	v_add_f32_e32 v113, v113, v114
	v_add_f32_e32 v114, v36, v37
	v_add_f32_e32 v115, v38, v39
	v_add_f32_e32 v114, v114, v115
	v_add_f32_e32 v112, v114, v112
	v_mul_f32_e32 v114, v37, v37
	v_mul_f32_e32 v115, v39, v39
	v_fmac_f32_e32 v114, v36, v36
	v_fmac_f32_e32 v115, v38, v38
	v_add_f32_e32 v114, v114, v115
	v_add_f32_e32 v113, v114, v113
	v_add_f32_e32 v114, v40, v41
	v_add_f32_e32 v115, v42, v43
	v_add_f32_e32 v114, v114, v115
	v_add_f32_e32 v112, v114, v112
	v_mul_f32_e32 v114, v41, v41
	v_mul_f32_e32 v115, v43, v43
	v_fmac_f32_e32 v114, v40, v40
	v_fmac_f32_e32 v115, v42, v42
	v_add_f32_e32 v114, v114, v115
	v_add_f32_e32 v113, v114, v113
	v_mov_b32_e32 v114, v112
	v_mov_b32_e32 v115, v113
	s_nop 0
	v_permlane16_swap_b32_e32 v112, v114
	v_permlane16_swap_b32_e32 v113, v115
	v_add_f32_e32 v112, v112, v114
	v_add_f32_e32 v113, v113, v115
	v_mov_b32_e32 v114, v112
	v_mov_b32_e32 v115, v113
	s_nop 0
	v_permlane32_swap_b32_e32 v112, v114
	v_permlane32_swap_b32_e32 v113, v115
	s_and_saveexec_b64 s[2:3], s[8:9]
	v_pk_add_f32 v[112:113], v[112:113], v[114:115]
	ds_write_b64 v184, v[112:113] offset:4608
	s_or_b64 exec, exec, s[2:3]
	v_add_f32_e32 v112, v28, v29
	v_add_f32_e32 v113, v30, v31
	v_add_f32_e32 v112, v112, v113
	v_mul_f32_e32 v113, v29, v29
	v_mul_f32_e32 v114, v31, v31
	v_fmac_f32_e32 v113, v28, v28
	v_fmac_f32_e32 v114, v30, v30
	v_add_f32_e32 v113, v113, v114
	v_add_f32_e32 v114, v32, v33
	v_add_f32_e32 v115, v34, v35
	v_add_f32_e32 v112, 0, v112
	v_add_f32_e32 v114, v114, v115
	v_add_f32_e32 v112, v114, v112
	v_mul_f32_e32 v114, v33, v33
	v_mul_f32_e32 v115, v35, v35
	v_fmac_f32_e32 v114, v32, v32
	v_fmac_f32_e32 v115, v34, v34
	v_add_f32_e32 v114, v114, v115
	v_add_f32_e32 v113, v113, v114
	v_add_f32_e32 v114, v20, v21
	v_add_f32_e32 v115, v22, v23
	v_add_f32_e32 v114, v114, v115
	v_add_f32_e32 v112, v114, v112
	v_mul_f32_e32 v114, v21, v21
	v_mul_f32_e32 v115, v23, v23
	v_fmac_f32_e32 v114, v20, v20
	v_fmac_f32_e32 v115, v22, v22
	v_add_f32_e32 v114, v114, v115
	v_add_f32_e32 v113, v114, v113
	v_add_f32_e32 v114, v24, v25
	v_add_f32_e32 v115, v26, v27
	v_add_f32_e32 v114, v114, v115
	v_add_f32_e32 v112, v114, v112
	v_mul_f32_e32 v114, v25, v25
	v_mul_f32_e32 v115, v27, v27
	v_fmac_f32_e32 v114, v24, v24
	v_fmac_f32_e32 v115, v26, v26
	v_add_f32_e32 v114, v114, v115
	v_add_f32_e32 v113, v114, v113
	v_mov_b32_e32 v114, v112
	v_mov_b32_e32 v115, v113
	s_nop 0
	v_permlane16_swap_b32_e32 v112, v114
	v_permlane16_swap_b32_e32 v113, v115
	v_add_f32_e32 v112, v112, v114
	v_add_f32_e32 v113, v113, v115
	v_mov_b32_e32 v114, v112
	v_mov_b32_e32 v115, v113
	s_nop 0
	v_permlane32_swap_b32_e32 v112, v114
	v_permlane32_swap_b32_e32 v113, v115
	s_and_saveexec_b64 s[2:3], s[8:9]
	v_pk_add_f32 v[112:113], v[112:113], v[114:115]
	ds_write_b64 v184, v[112:113] offset:5120
	s_or_b64 exec, exec, s[2:3]
	v_add_f32_e32 v112, v12, v13
	v_add_f32_e32 v113, v14, v15
	v_add_f32_e32 v112, v112, v113
	v_mul_f32_e32 v113, v13, v13
	v_mul_f32_e32 v114, v15, v15
	v_fmac_f32_e32 v113, v12, v12
	v_fmac_f32_e32 v114, v14, v14
	v_add_f32_e32 v113, v113, v114
	v_add_f32_e32 v114, v16, v17
	v_add_f32_e32 v115, v18, v19
	v_add_f32_e32 v112, 0, v112
	v_add_f32_e32 v114, v114, v115
	v_add_f32_e32 v112, v114, v112
	v_mul_f32_e32 v114, v17, v17
	v_mul_f32_e32 v115, v19, v19
	v_fmac_f32_e32 v114, v16, v16
	v_fmac_f32_e32 v115, v18, v18
	v_add_f32_e32 v114, v114, v115
	v_add_f32_e32 v113, v113, v114
	v_add_f32_e32 v114, v4, v5
	v_add_f32_e32 v115, v6, v7
	v_add_f32_e32 v114, v114, v115
	v_add_f32_e32 v112, v114, v112
	v_mul_f32_e32 v114, v5, v5
	v_mul_f32_e32 v115, v7, v7
	v_fmac_f32_e32 v114, v4, v4
	v_fmac_f32_e32 v115, v6, v6
	v_add_f32_e32 v114, v114, v115
	v_add_f32_e32 v113, v114, v113
	v_add_f32_e32 v114, v8, v9
	v_add_f32_e32 v115, v10, v11
	v_add_f32_e32 v114, v114, v115
	v_add_f32_e32 v112, v114, v112
	v_mul_f32_e32 v114, v9, v9
	v_mul_f32_e32 v115, v11, v11
	v_fmac_f32_e32 v114, v8, v8
	v_fmac_f32_e32 v115, v10, v10
	v_add_f32_e32 v114, v114, v115
	v_add_f32_e32 v113, v114, v113
	v_mov_b32_e32 v114, v112
	v_mov_b32_e32 v115, v113
	s_nop 0
	v_permlane16_swap_b32_e32 v112, v114
	v_permlane16_swap_b32_e32 v113, v115
	v_add_f32_e32 v112, v112, v114
	v_add_f32_e32 v113, v113, v115
	v_mov_b32_e32 v114, v112
	v_mov_b32_e32 v115, v113
	s_nop 0
	v_permlane32_swap_b32_e32 v112, v114
	v_permlane32_swap_b32_e32 v113, v115
	s_and_saveexec_b64 s[2:3], s[8:9]
	v_pk_add_f32 v[112:113], v[112:113], v[114:115]
	ds_write_b64 v184, v[112:113] offset:5632
	s_or_b64 exec, exec, s[2:3]
	s_waitcnt lgkmcnt(0)
	s_barrier
	s_add_u32 s14, s22, 0xac00000
	v_add_u32_e32 v170, s66, v180
	s_addc_u32 s15, s23, 0
	v_ashrrev_i32_e32 v171, 31, v170
	s_and_saveexec_b64 s[2:3], s[10:11]
	s_cbranch_execz .LBB0_257
	ds_read_b128 v[112:115], v183
	ds_read_b128 v[120:123], v183 offset:16
	s_ashr_i32 s83, s82, 31
	s_waitcnt lgkmcnt(1)
	v_mov_b32_e32 v124, v112
	s_waitcnt lgkmcnt(0)
	v_mov_b32_e32 v125, v120
	v_mov_b32_e32 v126, v114
	v_mov_b32_e32 v127, v122
	v_pk_add_f32 v[124:125], v[124:125], v[126:127]
	v_mov_b32_e32 v120, v113
	v_mov_b32_e32 v122, v115
	v_add_f32_e32 v114, v124, v125
	v_pk_add_f32 v[112:113], v[120:121], v[122:123]
	s_nop 0
	v_add_f32_e32 v113, v112, v113
	v_mul_f32_e32 v112, 0x3b800000, v114
	v_fma_f32 v113, -v114, v112, v113
	v_lshlrev_b64 v[114:115], 6, v[170:171]
	v_lshl_add_u64 v[114:115], s[14:15], 0, v[114:115]
	v_max_f32_e32 v113, 0, v113
	v_lshl_add_u64 v[114:115], s[82:83], 3, v[114:115]
	global_store_dwordx2 v[114:115], v[112:113], off sc1

.LBB0_344:
	v_mov_b32_e32 v143, v144
	v_mov_b32_e32 v144, v149
	v_mov_b32_e32 v142, v148
	v_pk_mul_f32 v[94:95], v[144:145], v[192:193]
	s_cmp_lt_i32 s14, 4
	v_pk_fma_f32 v[94:95], v[142:143], v[188:189], v[94:95] neg_lo:[0,0,1] neg_hi:[0,0,1]
	v_pk_mul_f32 v[142:143], v[142:143], v[192:193]
	s_cselect_b64 vcc, -1, 0
	v_pk_fma_f32 v[148:149], v[144:145], v[188:189], v[142:143]
	v_mov_b32_e32 v143, v146
	v_mov_b32_e32 v146, v151
	v_mov_b32_e32 v2, 0x3e38aa3b
	s_and_b32 s7, s14, -4
	v_mov_b32_e32 v142, v150
	v_pk_mul_f32 v[144:145], v[146:147], v[178:179]
	v_cndmask_b32_e32 v186, 1.0, v2, vcc
	s_cmp_eq_u32 s7, 4
	v_pk_fma_f32 v[150:151], v[142:143], v[238:239], v[144:145] neg_lo:[0,0,1] neg_hi:[0,0,1]
	v_pk_mul_f32 v[142:143], v[142:143], v[178:179]
	s_cselect_b64 s[26:27], -1, 0
	s_cmp_lg_u32 s7, 4
	v_pk_fma_f32 v[146:147], v[146:147], v[238:239], v[142:143]
	v_mul_f32_e32 v2, v186, v94
	v_mul_f32_e32 v142, v186, v148
	s_cselect_b64 s[22:23], -1, 0
	v_cvt_pk_bf16_f32 v142, v2, v142
	v_mul_f32_e32 v2, v186, v150
	v_mul_f32_e32 v143, v186, v146
	v_cvt_pk_bf16_f32 v143, v2, v143
	v_mul_f32_e32 v2, v186, v95
	v_mul_f32_e32 v144, v186, v149
	v_mul_f32_e32 v145, v186, v147
	s_and_b64 vcc, exec, s[22:23]
	s_mov_b32 s50, 0x18000
	s_mov_b32 s51, 0x1a000
	s_mov_b32 s52, 0xa000
	s_movk_i32 s53, 0x1000
	v_cvt_pk_bf16_f32 v144, v2, v144
	v_mul_f32_e32 v2, v186, v151
	v_cvt_pk_bf16_f32 v145, v2, v145
	s_cbranch_vccnz .LBB0_346
	v_pk_mul_f32 v[148:149], v[148:149], v[148:149]
	v_pk_mul_f32 v[146:147], v[146:147], v[146:147]
	v_pk_fma_f32 v[94:95], v[94:95], v[94:95], v[148:149]
	v_pk_fma_f32 v[146:147], v[150:151], v[150:151], v[146:147]
	s_nop 0
	v_pk_add_f32 v[94:95], v[94:95], v[146:147]
	s_nop 0
	v_add_f32_e32 v2, v94, v95
	v_mov_b32_e32 v94, v2
	s_nop 1
	v_permlane16_swap_b32_e32 v2, v94
	s_waitcnt lgkmcnt(0)
	v_add_f32_e32 v2, v2, v94
	v_mov_b32_e32 v94, v2
	s_nop 1
	v_permlane32_swap_b32_e32 v2, v94
	v_add_f32_e32 v2, v2, v94
	v_max_f32_e32 v2, 0, v2
	s_branch .LBB0_347

.LBB0_347:
	s_ashr_i32 s15, s14, 31
	s_lshl_b64 s[12:13], s[14:15], 25
	v_ashrrev_i32_e32 v225, 31, v224
	s_add_u32 s24, s41, s12
	s_addc_u32 s25, s42, s13
	v_lshlrev_b64 v[146:147], 9, v[224:225]
	v_mov_b64_e32 v[94:95], v[2:3]
	v_lshl_add_u64 v[146:147], s[24:25], 0, v[146:147]
	v_lshlrev_b32_e32 v2, 1, v214
	v_lshl_add_u64 v[146:147], v[146:147], 0, v[2:3]
	global_store_dwordx4 v[146:147], v[142:145], off
	v_cndmask_b32_e64 v149, 0, 1, s[26:27]
	v_cmp_ne_u32_e64 s[12:13], 1, v149
	v_mov_b32_e32 v143, v128
	v_mov_b32_e32 v128, v137
	v_mov_b32_e32 v142, v136
	v_pk_mul_f32 v[136:137], v[128:129], v[192:193]
	s_andn2_b64 vcc, exec, s[26:27]
	v_pk_fma_f32 v[136:137], v[142:143], v[188:189], v[136:137] neg_lo:[0,0,1] neg_hi:[0,0,1]
	v_pk_mul_f32 v[142:143], v[142:143], v[192:193]
	s_nop 0
	v_pk_fma_f32 v[142:143], v[128:129], v[188:189], v[142:143]
	v_mov_b32_e32 v129, v130
	v_mov_b32_e32 v130, v139
	v_mov_b32_e32 v128, v138
	v_pk_mul_f32 v[138:139], v[130:131], v[178:179]
	s_nop 0
	v_pk_fma_f32 v[138:139], v[128:129], v[238:239], v[138:139] neg_lo:[0,0,1] neg_hi:[0,0,1]
	v_pk_mul_f32 v[128:129], v[128:129], v[178:179]
	s_nop 0
	v_pk_fma_f32 v[144:145], v[130:131], v[238:239], v[128:129]
	v_mul_f32_e32 v128, v186, v136
	v_mul_f32_e32 v129, v186, v142
	v_cvt_pk_bf16_f32 v128, v128, v129
	v_mul_f32_e32 v129, v186, v138
	v_mul_f32_e32 v130, v186, v144
	v_cvt_pk_bf16_f32 v129, v129, v130
	v_mul_f32_e32 v130, v186, v137
	v_mul_f32_e32 v131, v186, v143
	v_cvt_pk_bf16_f32 v130, v130, v131
	v_mul_f32_e32 v131, v186, v139
	v_mul_f32_e32 v148, v186, v145
	v_cvt_pk_bf16_f32 v131, v131, v148
	s_cbranch_vccnz .LBB0_349
	v_pk_mul_f32 v[142:143], v[142:143], v[142:143]
	v_pk_mul_f32 v[144:145], v[144:145], v[144:145]
	v_pk_fma_f32 v[136:137], v[136:137], v[136:137], v[142:143]
	v_pk_fma_f32 v[138:139], v[138:139], v[138:139], v[144:145]
	v_max_f32_e32 v95, v95, v95
	v_pk_add_f32 v[136:137], v[136:137], v[138:139]
	s_nop 0
	v_add_f32_e32 v136, v136, v137
	v_mov_b32_e32 v137, v136
	s_nop 1
	v_permlane16_swap_b32_e32 v136, v137
	s_waitcnt lgkmcnt(0)
	v_add_f32_e32 v136, v136, v137
	v_mov_b32_e32 v137, v136
	s_nop 1
	v_permlane32_swap_b32_e32 v136, v137
	v_add_f32_e32 v136, v136, v137
	v_max_f32_e32 v95, v95, v136
.LBB0_349:
	global_store_dwordx4 v[146:147], v[128:131], off offset:256
	s_and_b64 vcc, exec, s[12:13]
	s_nop 0
	v_mov_b32_e32 v129, v116
	v_mov_b32_e32 v116, v125
	v_mov_b32_e32 v128, v124
	v_pk_mul_f32 v[124:125], v[116:117], v[184:185]
	s_nop 0
	v_pk_fma_f32 v[124:125], v[128:129], v[180:181], v[124:125] neg_lo:[0,0,1] neg_hi:[0,0,1]
	v_pk_mul_f32 v[128:129], v[128:129], v[184:185]
	s_nop 0
	v_pk_fma_f32 v[128:129], v[116:117], v[180:181], v[128:129]
	v_mov_b32_e32 v117, v118
	v_mov_b32_e32 v118, v127
	v_mov_b32_e32 v116, v126
	v_pk_mul_f32 v[126:127], v[118:119], v[98:99]
	s_nop 0
	v_pk_fma_f32 v[126:127], v[116:117], v[236:237], v[126:127] neg_lo:[0,0,1] neg_hi:[0,0,1]
	v_pk_mul_f32 v[116:117], v[116:117], v[98:99]
	s_nop 0
	v_pk_fma_f32 v[130:131], v[118:119], v[236:237], v[116:117]
	v_mul_f32_e32 v116, v186, v124
	v_mul_f32_e32 v117, v186, v128
	v_cvt_pk_bf16_f32 v116, v116, v117
	v_mul_f32_e32 v117, v186, v126
	v_mul_f32_e32 v118, v186, v130
	v_cvt_pk_bf16_f32 v117, v117, v118
	v_mul_f32_e32 v118, v186, v125
	v_mul_f32_e32 v119, v186, v129
	v_cvt_pk_bf16_f32 v118, v118, v119
	v_mul_f32_e32 v119, v186, v127
	v_mul_f32_e32 v136, v186, v131
	v_cvt_pk_bf16_f32 v119, v119, v136
	s_cbranch_vccnz .LBB0_351
	v_pk_mul_f32 v[128:129], v[128:129], v[128:129]
	v_pk_mul_f32 v[130:131], v[130:131], v[130:131]
	v_pk_fma_f32 v[124:125], v[124:125], v[124:125], v[128:129]
	v_pk_fma_f32 v[126:127], v[126:127], v[126:127], v[130:131]
	v_max_f32_e32 v94, v94, v94
	v_pk_add_f32 v[124:125], v[124:125], v[126:127]
	s_nop 0
	v_add_f32_e32 v124, v124, v125
	v_mov_b32_e32 v125, v124
	s_nop 1
	v_permlane16_swap_b32_e32 v124, v125
	s_waitcnt lgkmcnt(0)
	v_add_f32_e32 v124, v124, v125
	v_mov_b32_e32 v125, v124
	s_nop 1
	v_permlane32_swap_b32_e32 v124, v125
	v_add_f32_e32 v124, v124, v125
	v_max_f32_e32 v94, v94, v124
.LBB0_351:
	v_ashrrev_i32_e32 v233, 31, v232
	v_lshlrev_b64 v[124:125], 9, v[232:233]
	v_lshl_add_u64 v[124:125], s[24:25], 0, v[124:125]
	v_lshl_add_u64 v[124:125], v[124:125], 0, v[2:3]
	global_store_dwordx4 v[124:125], v[116:119], off
	s_and_b64 vcc, exec, s[12:13]
	s_nop 0
	v_mov_b32_e32 v117, v108
	v_mov_b32_e32 v108, v113
	v_mov_b32_e32 v116, v112
	v_pk_mul_f32 v[112:113], v[108:109], v[184:185]
	s_nop 0
	v_pk_fma_f32 v[112:113], v[116:117], v[180:181], v[112:113] neg_lo:[0,0,1] neg_hi:[0,0,1]
	v_pk_mul_f32 v[116:117], v[116:117], v[184:185]
	s_nop 0
	v_pk_fma_f32 v[116:117], v[108:109], v[180:181], v[116:117]
	v_mov_b32_e32 v108, v114
	v_mov_b32_e32 v109, v110
	v_mov_b32_e32 v110, v115
	v_pk_mul_f32 v[114:115], v[110:111], v[98:99]
	v_pk_mul_f32 v[98:99], v[108:109], v[98:99]
	v_pk_fma_f32 v[114:115], v[108:109], v[236:237], v[114:115] neg_lo:[0,0,1] neg_hi:[0,0,1]
	v_pk_fma_f32 v[98:99], v[110:111], v[236:237], v[98:99]
	v_mul_f32_e32 v108, v186, v112
	v_mul_f32_e32 v109, v186, v116
	v_cvt_pk_bf16_f32 v108, v108, v109
	v_mul_f32_e32 v109, v186, v114
	v_mul_f32_e32 v110, v186, v98
	v_cvt_pk_bf16_f32 v109, v109, v110
	v_mul_f32_e32 v110, v186, v113
	v_mul_f32_e32 v111, v186, v117
	v_cvt_pk_bf16_f32 v110, v110, v111
	v_mul_f32_e32 v111, v186, v115
	v_mul_f32_e32 v118, v186, v99
	v_cvt_pk_bf16_f32 v111, v111, v118
	s_cbranch_vccnz .LBB0_353
	v_pk_mul_f32 v[116:117], v[116:117], v[116:117]
	v_pk_mul_f32 v[98:99], v[98:99], v[98:99]
	v_pk_fma_f32 v[112:113], v[112:113], v[112:113], v[116:117]
	v_pk_fma_f32 v[98:99], v[114:115], v[114:115], v[98:99]
	v_max_f32_e32 v95, v95, v95
	v_pk_add_f32 v[98:99], v[112:113], v[98:99]
	s_nop 0
	v_add_f32_e32 v98, v98, v99
	v_mov_b32_e32 v99, v98
	s_nop 1
	v_permlane16_swap_b32_e32 v98, v99
	s_waitcnt lgkmcnt(0)
	v_add_f32_e32 v98, v98, v99
	v_mov_b32_e32 v99, v98
	s_nop 1
	v_permlane32_swap_b32_e32 v98, v99
	v_add_f32_e32 v98, v98, v99
	v_max_f32_e32 v95, v95, v98
.LBB0_353:
	v_mov_b32_e32 v99, v100
	v_mov_b32_e32 v100, v105
	v_mov_b32_e32 v98, v104
	v_pk_mul_f32 v[104:105], v[100:101], v[176:177]
	global_store_dwordx4 v[124:125], v[108:111], off offset:256
	v_pk_fma_f32 v[104:105], v[98:99], v[172:173], v[104:105] neg_lo:[0,0,1] neg_hi:[0,0,1]
	v_pk_mul_f32 v[98:99], v[98:99], v[176:177]
	s_and_b64 vcc, exec, s[12:13]
	v_pk_fma_f32 v[108:109], v[100:101], v[172:173], v[98:99]
	v_mov_b32_e32 v99, v102
	v_mov_b32_e32 v102, v107
	v_mov_b32_e32 v98, v106
	v_pk_mul_f32 v[100:101], v[102:103], v[170:171]
	s_nop 0
	v_pk_fma_f32 v[106:107], v[98:99], v[234:235], v[100:101] neg_lo:[0,0,1] neg_hi:[0,0,1]
	v_pk_mul_f32 v[98:99], v[98:99], v[170:171]
	v_mul_f32_e32 v101, v186, v109
	v_pk_fma_f32 v[102:103], v[102:103], v[234:235], v[98:99]
	v_mul_f32_e32 v98, v186, v104
	v_mul_f32_e32 v99, v186, v108
	v_cvt_pk_bf16_f32 v98, v98, v99
	v_mul_f32_e32 v99, v186, v106
	v_mul_f32_e32 v100, v186, v102
	v_cvt_pk_bf16_f32 v99, v99, v100
	v_mul_f32_e32 v100, v186, v105
	v_cvt_pk_bf16_f32 v100, v100, v101
	v_mul_f32_e32 v101, v186, v107
	v_mul_f32_e32 v110, v186, v103
	v_cvt_pk_bf16_f32 v101, v101, v110
	s_cbranch_vccnz .LBB0_355
	v_pk_mul_f32 v[108:109], v[108:109], v[108:109]
	v_pk_mul_f32 v[102:103], v[102:103], v[102:103]
	v_pk_fma_f32 v[104:105], v[104:105], v[104:105], v[108:109]
	v_pk_fma_f32 v[102:103], v[106:107], v[106:107], v[102:103]
	v_max_f32_e32 v94, v94, v94
	v_pk_add_f32 v[102:103], v[104:105], v[102:103]
	s_nop 0
	v_add_f32_e32 v102, v102, v103
	v_mov_b32_e32 v103, v102
	s_nop 1
	v_permlane16_swap_b32_e32 v102, v103
	s_waitcnt lgkmcnt(0)
	v_add_f32_e32 v102, v102, v103
	v_mov_b32_e32 v103, v102
	s_nop 1
	v_permlane32_swap_b32_e32 v102, v103
	v_add_f32_e32 v102, v102, v103
	v_max_f32_e32 v94, v94, v102
.LBB0_355:
	v_ashrrev_i32_e32 v229, 31, v228
	v_lshlrev_b64 v[102:103], 9, v[228:229]
	v_lshl_add_u64 v[102:103], s[24:25], 0, v[102:103]
	v_lshl_add_u64 v[102:103], v[102:103], 0, v[2:3]
	global_store_dwordx4 v[102:103], v[98:101], off
	s_and_b64 vcc, exec, s[12:13]
	s_nop 0
	v_mov_b32_e32 v99, v84
	v_mov_b32_e32 v84, v89
	v_mov_b32_e32 v98, v88
	v_pk_mul_f32 v[88:89], v[84:85], v[176:177]
	s_nop 0
	v_pk_fma_f32 v[88:89], v[98:99], v[172:173], v[88:89] neg_lo:[0,0,1] neg_hi:[0,0,1]
	v_pk_mul_f32 v[98:99], v[98:99], v[176:177]
	s_nop 0
	v_pk_fma_f32 v[98:99], v[84:85], v[172:173], v[98:99]
	v_mov_b32_e32 v85, v86
	v_mov_b32_e32 v86, v91
	v_mov_b32_e32 v84, v90
	v_pk_mul_f32 v[90:91], v[86:87], v[170:171]
	s_nop 0
	v_pk_fma_f32 v[90:91], v[84:85], v[234:235], v[90:91] neg_lo:[0,0,1] neg_hi:[0,0,1]
	v_pk_mul_f32 v[84:85], v[84:85], v[170:171]
	s_nop 0
	v_pk_fma_f32 v[100:101], v[86:87], v[234:235], v[84:85]
	v_mul_f32_e32 v84, v186, v88
	v_mul_f32_e32 v85, v186, v98
	v_cvt_pk_bf16_f32 v84, v84, v85
	v_mul_f32_e32 v85, v186, v90
	v_mul_f32_e32 v86, v186, v100
	v_cvt_pk_bf16_f32 v85, v85, v86
	v_mul_f32_e32 v86, v186, v89
	v_mul_f32_e32 v87, v186, v99
	v_cvt_pk_bf16_f32 v86, v86, v87
	v_mul_f32_e32 v87, v186, v91
	v_mul_f32_e32 v104, v186, v101
	v_cvt_pk_bf16_f32 v87, v87, v104
	s_cbranch_vccnz .LBB0_357
	v_pk_mul_f32 v[98:99], v[98:99], v[98:99]
	v_pk_mul_f32 v[100:101], v[100:101], v[100:101]
	v_pk_fma_f32 v[88:89], v[88:89], v[88:89], v[98:99]
	v_pk_fma_f32 v[90:91], v[90:91], v[90:91], v[100:101]
	s_nop 0
	v_pk_add_f32 v[88:89], v[88:89], v[90:91]
	s_nop 0
	v_add_f32_e32 v88, v88, v89
	v_mov_b32_e32 v89, v88
	s_nop 1
	v_permlane16_swap_b32_e32 v88, v89
	s_waitcnt lgkmcnt(0)
	v_add_f32_e32 v88, v88, v89
	v_mov_b32_e32 v89, v88
	s_nop 1
	v_permlane32_swap_b32_e32 v88, v89
	v_add_f32_e32 v88, v88, v89
	v_max_f32_e32 v89, v95, v95
	v_max_f32_e32 v95, v89, v88
.LBB0_357:
	global_store_dwordx4 v[102:103], v[84:87], off offset:256
	s_and_b64 vcc, exec, s[12:13]
	s_nop 0
	v_mov_b32_e32 v85, v76
	v_mov_b32_e32 v76, v81
	v_mov_b32_e32 v84, v80
	v_pk_mul_f32 v[80:81], v[76:77], v[168:169]
	s_nop 0
	v_pk_fma_f32 v[80:81], v[84:85], v[164:165], v[80:81] neg_lo:[0,0,1] neg_hi:[0,0,1]
	v_pk_mul_f32 v[84:85], v[84:85], v[168:169]
	s_nop 0
	v_pk_fma_f32 v[84:85], v[76:77], v[164:165], v[84:85]
	v_mov_b32_e32 v77, v78
	v_mov_b32_e32 v78, v83
	v_mov_b32_e32 v76, v82
	v_pk_mul_f32 v[82:83], v[78:79], v[162:163]
	s_nop 0
	v_pk_fma_f32 v[82:83], v[76:77], v[230:231], v[82:83] neg_lo:[0,0,1] neg_hi:[0,0,1]
	v_pk_mul_f32 v[76:77], v[76:77], v[162:163]
	s_nop 0
	v_pk_fma_f32 v[86:87], v[78:79], v[230:231], v[76:77]
	v_mul_f32_e32 v76, v186, v80
	v_mul_f32_e32 v77, v186, v84
	v_cvt_pk_bf16_f32 v76, v76, v77
	v_mul_f32_e32 v77, v186, v82
	v_mul_f32_e32 v78, v186, v86
	v_cvt_pk_bf16_f32 v77, v77, v78
	v_mul_f32_e32 v78, v186, v81
	v_mul_f32_e32 v79, v186, v85
	v_cvt_pk_bf16_f32 v78, v78, v79
	v_mul_f32_e32 v79, v186, v83
	v_mul_f32_e32 v88, v186, v87
	v_cvt_pk_bf16_f32 v79, v79, v88
	s_cbranch_vccnz .LBB0_359
	v_pk_mul_f32 v[84:85], v[84:85], v[84:85]
	v_pk_mul_f32 v[86:87], v[86:87], v[86:87]
	v_pk_fma_f32 v[80:81], v[80:81], v[80:81], v[84:85]
	v_pk_fma_f32 v[82:83], v[82:83], v[82:83], v[86:87]
	s_nop 0
	v_pk_add_f32 v[80:81], v[80:81], v[82:83]
	s_nop 0
	v_add_f32_e32 v80, v80, v81
	v_mov_b32_e32 v81, v80
	s_nop 1
	v_permlane16_swap_b32_e32 v80, v81
	s_waitcnt lgkmcnt(0)
	v_add_f32_e32 v80, v80, v81
	v_mov_b32_e32 v81, v80
	s_nop 1
	v_permlane32_swap_b32_e32 v80, v81
	v_add_f32_e32 v80, v80, v81
	v_max_f32_e32 v81, v94, v94
	v_max_f32_e32 v94, v81, v80
.LBB0_359:
	v_ashrrev_i32_e32 v227, 31, v226
	v_lshlrev_b64 v[80:81], 9, v[226:227]
	v_lshl_add_u64 v[80:81], s[24:25], 0, v[80:81]
	v_lshl_add_u64 v[80:81], v[80:81], 0, v[2:3]
	global_store_dwordx4 v[80:81], v[76:79], off
	s_and_b64 vcc, exec, s[12:13]
	s_nop 0
	v_mov_b32_e32 v77, v68
	v_mov_b32_e32 v68, v73
	v_mov_b32_e32 v76, v72
	v_pk_mul_f32 v[72:73], v[68:69], v[168:169]
	s_nop 0
	v_pk_fma_f32 v[72:73], v[76:77], v[164:165], v[72:73] neg_lo:[0,0,1] neg_hi:[0,0,1]
	v_pk_mul_f32 v[76:77], v[76:77], v[168:169]
	s_nop 0
	v_pk_fma_f32 v[76:77], v[68:69], v[164:165], v[76:77]
	v_mov_b32_e32 v69, v70
	v_mov_b32_e32 v70, v75
	v_mov_b32_e32 v68, v74
	v_pk_mul_f32 v[74:75], v[70:71], v[162:163]
	s_nop 0
	v_pk_fma_f32 v[74:75], v[68:69], v[230:231], v[74:75] neg_lo:[0,0,1] neg_hi:[0,0,1]
	v_pk_mul_f32 v[68:69], v[68:69], v[162:163]
	s_nop 0
	v_pk_fma_f32 v[78:79], v[70:71], v[230:231], v[68:69]
	v_mul_f32_e32 v68, v186, v72
	v_mul_f32_e32 v69, v186, v76
	v_cvt_pk_bf16_f32 v68, v68, v69
	v_mul_f32_e32 v69, v186, v74
	v_mul_f32_e32 v70, v186, v78
	v_cvt_pk_bf16_f32 v69, v69, v70
	v_mul_f32_e32 v70, v186, v73
	v_mul_f32_e32 v71, v186, v77
	v_cvt_pk_bf16_f32 v70, v70, v71
	v_mul_f32_e32 v71, v186, v75
	v_mul_f32_e32 v82, v186, v79
	v_cvt_pk_bf16_f32 v71, v71, v82
	s_cbranch_vccnz .LBB0_361
	v_pk_mul_f32 v[76:77], v[76:77], v[76:77]
	v_pk_mul_f32 v[78:79], v[78:79], v[78:79]
	v_pk_fma_f32 v[72:73], v[72:73], v[72:73], v[76:77]
	v_pk_fma_f32 v[74:75], v[74:75], v[74:75], v[78:79]
	s_nop 0
	v_pk_add_f32 v[72:73], v[72:73], v[74:75]
	s_nop 0
	v_add_f32_e32 v72, v72, v73
	v_mov_b32_e32 v73, v72
	s_nop 1
	v_permlane16_swap_b32_e32 v72, v73
	s_waitcnt lgkmcnt(0)
	v_add_f32_e32 v72, v72, v73
	v_mov_b32_e32 v73, v72
	s_nop 1
	v_permlane32_swap_b32_e32 v72, v73
	v_add_f32_e32 v72, v72, v73
	v_max_f32_e32 v73, v95, v95
	v_max_f32_e32 v95, v73, v72
.LBB0_361:
	global_store_dwordx4 v[80:81], v[68:71], off offset:256
	s_and_b64 vcc, exec, s[12:13]
	s_nop 0
	v_mov_b32_e32 v69, v60
	v_mov_b32_e32 v60, v65
	v_mov_b32_e32 v68, v64
	v_pk_mul_f32 v[64:65], v[60:61], v[160:161]
	s_nop 0
	v_pk_fma_f32 v[64:65], v[68:69], v[156:157], v[64:65] neg_lo:[0,0,1] neg_hi:[0,0,1]
	v_pk_mul_f32 v[68:69], v[68:69], v[160:161]
	s_nop 0
	v_pk_fma_f32 v[68:69], v[60:61], v[156:157], v[68:69]
	v_mov_b32_e32 v61, v62
	v_mov_b32_e32 v62, v67
	v_mov_b32_e32 v60, v66
	v_pk_mul_f32 v[66:67], v[62:63], v[154:155]
	s_nop 0
	v_pk_fma_f32 v[66:67], v[60:61], v[190:191], v[66:67] neg_lo:[0,0,1] neg_hi:[0,0,1]
	v_pk_mul_f32 v[60:61], v[60:61], v[154:155]
	s_nop 0
	v_pk_fma_f32 v[70:71], v[62:63], v[190:191], v[60:61]
	v_mul_f32_e32 v60, v186, v64
	v_mul_f32_e32 v61, v186, v68
	v_cvt_pk_bf16_f32 v60, v60, v61
	v_mul_f32_e32 v61, v186, v66
	v_mul_f32_e32 v62, v186, v70
	v_cvt_pk_bf16_f32 v61, v61, v62
	v_mul_f32_e32 v62, v186, v65
	v_mul_f32_e32 v63, v186, v69
	v_cvt_pk_bf16_f32 v62, v62, v63
	v_mul_f32_e32 v63, v186, v67
	v_mul_f32_e32 v72, v186, v71
	v_cvt_pk_bf16_f32 v63, v63, v72
	s_cbranch_vccnz .LBB0_363
	v_pk_mul_f32 v[68:69], v[68:69], v[68:69]
	v_pk_mul_f32 v[70:71], v[70:71], v[70:71]
	v_pk_fma_f32 v[64:65], v[64:65], v[64:65], v[68:69]
	v_pk_fma_f32 v[66:67], v[66:67], v[66:67], v[70:71]
	s_nop 0
	v_pk_add_f32 v[64:65], v[64:65], v[66:67]
	s_nop 0
	v_add_f32_e32 v64, v64, v65
	v_mov_b32_e32 v65, v64
	s_nop 1
	v_permlane16_swap_b32_e32 v64, v65
	s_waitcnt lgkmcnt(0)
	v_add_f32_e32 v64, v64, v65
	v_mov_b32_e32 v65, v64
	s_nop 1
	v_permlane32_swap_b32_e32 v64, v65
	v_add_f32_e32 v64, v64, v65
	v_max_f32_e32 v65, v94, v94
	v_max_f32_e32 v94, v65, v64
.LBB0_363:
	v_lshlrev_b64 v[64:65], 9, v[224:225]
	v_lshl_add_u64 v[64:65], s[24:25], 0, v[64:65]
	v_lshl_add_u64 v[64:65], v[64:65], 0, v[2:3]
	v_add_co_u32_e32 v66, vcc, 0x10000, v64
	s_nop 1
	v_addc_co_u32_e32 v67, vcc, 0, v65, vcc
	global_store_dwordx4 v[66:67], v[60:63], off
	s_and_b64 vcc, exec, s[12:13]
	s_nop 0
	v_mov_b32_e32 v61, v52
	v_mov_b32_e32 v52, v57
	v_mov_b32_e32 v60, v56
	v_pk_mul_f32 v[56:57], v[52:53], v[160:161]
	s_nop 0
	v_pk_fma_f32 v[56:57], v[60:61], v[156:157], v[56:57] neg_lo:[0,0,1] neg_hi:[0,0,1]
	v_pk_mul_f32 v[60:61], v[60:61], v[160:161]
	s_nop 0
	v_pk_fma_f32 v[60:61], v[52:53], v[156:157], v[60:61]
	v_mov_b32_e32 v53, v54
	v_mov_b32_e32 v54, v59
	v_mov_b32_e32 v52, v58
	v_pk_mul_f32 v[58:59], v[54:55], v[154:155]
	s_nop 0
	v_pk_fma_f32 v[58:59], v[52:53], v[190:191], v[58:59] neg_lo:[0,0,1] neg_hi:[0,0,1]
	v_pk_mul_f32 v[52:53], v[52:53], v[154:155]
	s_nop 0
	v_pk_fma_f32 v[62:63], v[54:55], v[190:191], v[52:53]
	v_mul_f32_e32 v52, v186, v56
	v_mul_f32_e32 v53, v186, v60
	v_cvt_pk_bf16_f32 v52, v52, v53
	v_mul_f32_e32 v53, v186, v58
	v_mul_f32_e32 v54, v186, v62
	v_cvt_pk_bf16_f32 v53, v53, v54
	v_mul_f32_e32 v54, v186, v57
	v_mul_f32_e32 v55, v186, v61
	v_cvt_pk_bf16_f32 v54, v54, v55
	v_mul_f32_e32 v55, v186, v59
	v_mul_f32_e32 v66, v186, v63
	v_cvt_pk_bf16_f32 v55, v55, v66
	s_cbranch_vccnz .LBB0_365
	v_pk_mul_f32 v[60:61], v[60:61], v[60:61]
	v_pk_mul_f32 v[62:63], v[62:63], v[62:63]
	v_pk_fma_f32 v[56:57], v[56:57], v[56:57], v[60:61]
	v_pk_fma_f32 v[58:59], v[58:59], v[58:59], v[62:63]
	s_nop 0
	v_pk_add_f32 v[56:57], v[56:57], v[58:59]
	s_nop 0
	v_add_f32_e32 v56, v56, v57
	v_mov_b32_e32 v57, v56
	s_nop 1
	v_permlane16_swap_b32_e32 v56, v57
	s_waitcnt lgkmcnt(0)
	v_add_f32_e32 v56, v56, v57
	v_mov_b32_e32 v57, v56
	s_nop 1
	v_permlane32_swap_b32_e32 v56, v57
	v_add_f32_e32 v56, v56, v57
	v_max_f32_e32 v57, v95, v95
	v_max_f32_e32 v95, v57, v56
.LBB0_365:
	v_lshl_add_u64 v[56:57], v[64:65], 0, s[76:77]
	global_store_dwordx4 v[56:57], v[52:55], off offset:256
	s_and_b64 vcc, exec, s[12:13]
	s_nop 0
	v_mov_b32_e32 v53, v44
	v_mov_b32_e32 v44, v49
	v_mov_b32_e32 v52, v48
	v_pk_mul_f32 v[48:49], v[44:45], v[152:153]
	s_nop 0
	v_pk_fma_f32 v[48:49], v[52:53], v[140:141], v[48:49] neg_lo:[0,0,1] neg_hi:[0,0,1]
	v_pk_mul_f32 v[52:53], v[52:53], v[152:153]
	s_nop 0
	v_pk_fma_f32 v[52:53], v[44:45], v[140:141], v[52:53]
	v_mov_b32_e32 v45, v46
	v_mov_b32_e32 v46, v51
	v_mov_b32_e32 v44, v50
	v_pk_mul_f32 v[50:51], v[46:47], v[134:135]
	s_nop 0
	v_pk_fma_f32 v[50:51], v[44:45], v[182:183], v[50:51] neg_lo:[0,0,1] neg_hi:[0,0,1]
	v_pk_mul_f32 v[44:45], v[44:45], v[134:135]
	s_nop 0
	v_pk_fma_f32 v[54:55], v[46:47], v[182:183], v[44:45]
	v_mul_f32_e32 v44, v186, v48
	v_mul_f32_e32 v45, v186, v52
	v_cvt_pk_bf16_f32 v44, v44, v45
	v_mul_f32_e32 v45, v186, v50
	v_mul_f32_e32 v46, v186, v54
	v_cvt_pk_bf16_f32 v45, v45, v46
	v_mul_f32_e32 v46, v186, v49
	v_mul_f32_e32 v47, v186, v53
	v_cvt_pk_bf16_f32 v46, v46, v47
	v_mul_f32_e32 v47, v186, v51
	v_mul_f32_e32 v56, v186, v55
	v_cvt_pk_bf16_f32 v47, v47, v56
	s_cbranch_vccnz .LBB0_367
	v_pk_mul_f32 v[52:53], v[52:53], v[52:53]
	v_pk_mul_f32 v[54:55], v[54:55], v[54:55]
	v_pk_fma_f32 v[48:49], v[48:49], v[48:49], v[52:53]
	v_pk_fma_f32 v[50:51], v[50:51], v[50:51], v[54:55]
	s_nop 0
	v_pk_add_f32 v[48:49], v[48:49], v[50:51]
	s_nop 0
	v_add_f32_e32 v48, v48, v49
	v_mov_b32_e32 v49, v48
	s_nop 1
	v_permlane16_swap_b32_e32 v48, v49
	s_waitcnt lgkmcnt(0)
	v_add_f32_e32 v48, v48, v49
	v_mov_b32_e32 v49, v48
	s_nop 1
	v_permlane32_swap_b32_e32 v48, v49
	v_add_f32_e32 v48, v48, v49
	v_max_f32_e32 v49, v94, v94
	v_max_f32_e32 v94, v49, v48
.LBB0_367:
	v_lshlrev_b64 v[48:49], 9, v[224:225]
	v_lshl_add_u64 v[48:49], s[24:25], 0, v[48:49]
	v_lshl_add_u64 v[48:49], v[48:49], 0, v[2:3]
	v_add_co_u32_e32 v50, vcc, 0x12000, v48
	s_nop 1
	v_addc_co_u32_e32 v51, vcc, 0, v49, vcc
	global_store_dwordx4 v[50:51], v[44:47], off
	s_and_b64 vcc, exec, s[12:13]
	s_nop 0
	v_mov_b32_e32 v45, v36
	v_mov_b32_e32 v36, v41
	v_mov_b32_e32 v44, v40
	v_pk_mul_f32 v[40:41], v[36:37], v[152:153]
	s_nop 0
	v_pk_fma_f32 v[40:41], v[44:45], v[140:141], v[40:41] neg_lo:[0,0,1] neg_hi:[0,0,1]
	v_pk_mul_f32 v[44:45], v[44:45], v[152:153]
	s_nop 0
	v_pk_fma_f32 v[44:45], v[36:37], v[140:141], v[44:45]
	v_mov_b32_e32 v37, v38
	v_mov_b32_e32 v38, v43
	v_mov_b32_e32 v36, v42
	v_pk_mul_f32 v[42:43], v[38:39], v[134:135]
	s_nop 0
	v_pk_fma_f32 v[42:43], v[36:37], v[182:183], v[42:43] neg_lo:[0,0,1] neg_hi:[0,0,1]
	v_pk_mul_f32 v[36:37], v[36:37], v[134:135]
	s_nop 0
	v_pk_fma_f32 v[46:47], v[38:39], v[182:183], v[36:37]
	v_mul_f32_e32 v36, v186, v40
	v_mul_f32_e32 v37, v186, v44
	v_cvt_pk_bf16_f32 v36, v36, v37
	v_mul_f32_e32 v37, v186, v42
	v_mul_f32_e32 v38, v186, v46
	v_cvt_pk_bf16_f32 v37, v37, v38
	v_mul_f32_e32 v38, v186, v41
	v_mul_f32_e32 v39, v186, v45
	v_cvt_pk_bf16_f32 v38, v38, v39
	v_mul_f32_e32 v39, v186, v43
	v_mul_f32_e32 v50, v186, v47
	v_cvt_pk_bf16_f32 v39, v39, v50
	s_cbranch_vccnz .LBB0_369
	v_pk_mul_f32 v[44:45], v[44:45], v[44:45]
	v_pk_mul_f32 v[46:47], v[46:47], v[46:47]
	v_pk_fma_f32 v[40:41], v[40:41], v[40:41], v[44:45]
	v_pk_fma_f32 v[42:43], v[42:43], v[42:43], v[46:47]
	s_nop 0
	v_pk_add_f32 v[40:41], v[40:41], v[42:43]
	s_nop 0
	v_add_f32_e32 v40, v40, v41
	v_mov_b32_e32 v41, v40
	s_nop 1
	v_permlane16_swap_b32_e32 v40, v41
	s_waitcnt lgkmcnt(0)
	v_add_f32_e32 v40, v40, v41
	v_mov_b32_e32 v41, v40
	s_nop 1
	v_permlane32_swap_b32_e32 v40, v41
	v_add_f32_e32 v40, v40, v41
	v_max_f32_e32 v41, v95, v95
	v_max_f32_e32 v95, v41, v40
.LBB0_369:
	s_mov_b64 s[26:27], 0x12000
	v_lshl_add_u64 v[40:41], v[48:49], 0, s[26:27]
	global_store_dwordx4 v[40:41], v[36:39], off offset:256
	s_and_b64 vcc, exec, s[12:13]
	s_nop 0
	v_mov_b32_e32 v37, v28
	v_mov_b32_e32 v28, v33
	v_mov_b32_e32 v36, v32
	v_pk_mul_f32 v[32:33], v[28:29], v[132:133]
	s_nop 0
	v_pk_fma_f32 v[32:33], v[36:37], v[120:121], v[32:33] neg_lo:[0,0,1] neg_hi:[0,0,1]
	v_pk_mul_f32 v[36:37], v[36:37], v[132:133]
	s_nop 0
	v_pk_fma_f32 v[36:37], v[28:29], v[120:121], v[36:37]
	v_mov_b32_e32 v29, v30
	v_mov_b32_e32 v30, v35
	v_mov_b32_e32 v28, v34
	v_pk_mul_f32 v[34:35], v[30:31], v[174:175]
	s_nop 0
	v_pk_fma_f32 v[34:35], v[28:29], v[166:167], v[34:35] neg_lo:[0,0,1] neg_hi:[0,0,1]
	v_pk_mul_f32 v[28:29], v[28:29], v[174:175]
	s_nop 0
	v_pk_fma_f32 v[38:39], v[30:31], v[166:167], v[28:29]
	v_mul_f32_e32 v28, v186, v32
	v_mul_f32_e32 v29, v186, v36
	v_cvt_pk_bf16_f32 v28, v28, v29
	v_mul_f32_e32 v29, v186, v34
	v_mul_f32_e32 v30, v186, v38
	v_cvt_pk_bf16_f32 v29, v29, v30
	v_mul_f32_e32 v30, v186, v33
	v_mul_f32_e32 v31, v186, v37
	v_cvt_pk_bf16_f32 v30, v30, v31
	v_mul_f32_e32 v31, v186, v35
	v_mul_f32_e32 v40, v186, v39
	v_cvt_pk_bf16_f32 v31, v31, v40
	s_cbranch_vccnz .LBB0_371
	v_pk_mul_f32 v[36:37], v[36:37], v[36:37]
	v_pk_mul_f32 v[38:39], v[38:39], v[38:39]
	v_pk_fma_f32 v[32:33], v[32:33], v[32:33], v[36:37]
	v_pk_fma_f32 v[34:35], v[34:35], v[34:35], v[38:39]
	s_nop 0
	v_pk_add_f32 v[32:33], v[32:33], v[34:35]
	s_nop 0
	v_add_f32_e32 v32, v32, v33
	v_mov_b32_e32 v33, v32
	s_nop 1
	v_permlane16_swap_b32_e32 v32, v33
	s_waitcnt lgkmcnt(0)
	v_add_f32_e32 v32, v32, v33
	v_mov_b32_e32 v33, v32
	s_nop 1
	v_permlane32_swap_b32_e32 v32, v33
	v_add_f32_e32 v32, v32, v33
	v_max_f32_e32 v33, v94, v94
	v_max_f32_e32 v94, v33, v32
.LBB0_371:
	v_lshlrev_b64 v[32:33], 9, v[224:225]
	v_lshl_add_u64 v[32:33], s[24:25], 0, v[32:33]
	v_lshl_add_u64 v[32:33], v[32:33], 0, v[2:3]
	v_add_co_u32_e32 v34, vcc, 0x14000, v32
	s_nop 1
	v_addc_co_u32_e32 v35, vcc, 0, v33, vcc
	global_store_dwordx4 v[34:35], v[28:31], off
	s_and_b64 vcc, exec, s[12:13]
	s_nop 0
	v_mov_b32_e32 v29, v20
	v_mov_b32_e32 v20, v25
	v_mov_b32_e32 v28, v24
	v_pk_mul_f32 v[24:25], v[20:21], v[132:133]
	s_nop 0
	v_pk_fma_f32 v[24:25], v[28:29], v[120:121], v[24:25] neg_lo:[0,0,1] neg_hi:[0,0,1]
	v_pk_mul_f32 v[28:29], v[28:29], v[132:133]
	s_nop 0
	v_pk_fma_f32 v[28:29], v[20:21], v[120:121], v[28:29]
	v_mov_b32_e32 v21, v22
	v_mov_b32_e32 v22, v27
	v_mov_b32_e32 v20, v26
	v_pk_mul_f32 v[26:27], v[22:23], v[174:175]
	s_nop 0
	v_pk_fma_f32 v[26:27], v[20:21], v[166:167], v[26:27] neg_lo:[0,0,1] neg_hi:[0,0,1]
	v_pk_mul_f32 v[20:21], v[20:21], v[174:175]
	s_nop 0
	v_pk_fma_f32 v[30:31], v[22:23], v[166:167], v[20:21]
	v_mul_f32_e32 v20, v186, v24
	v_mul_f32_e32 v21, v186, v28
	v_cvt_pk_bf16_f32 v20, v20, v21
	v_mul_f32_e32 v21, v186, v26
	v_mul_f32_e32 v22, v186, v30
	v_cvt_pk_bf16_f32 v21, v21, v22
	v_mul_f32_e32 v22, v186, v25
	v_mul_f32_e32 v23, v186, v29
	v_cvt_pk_bf16_f32 v22, v22, v23
	v_mul_f32_e32 v23, v186, v27
	v_mul_f32_e32 v34, v186, v31
	v_cvt_pk_bf16_f32 v23, v23, v34
	s_cbranch_vccnz .LBB0_373
	v_pk_mul_f32 v[28:29], v[28:29], v[28:29]
	v_pk_mul_f32 v[30:31], v[30:31], v[30:31]
	v_pk_fma_f32 v[24:25], v[24:25], v[24:25], v[28:29]
	v_pk_fma_f32 v[26:27], v[26:27], v[26:27], v[30:31]
	s_nop 0
	v_pk_add_f32 v[24:25], v[24:25], v[26:27]
	s_nop 0
	v_add_f32_e32 v24, v24, v25
	v_mov_b32_e32 v25, v24
	s_nop 1
	v_permlane16_swap_b32_e32 v24, v25
	s_waitcnt lgkmcnt(0)
	v_add_f32_e32 v24, v24, v25
	v_mov_b32_e32 v25, v24
	s_nop 1
	v_permlane32_swap_b32_e32 v24, v25
	v_add_f32_e32 v24, v24, v25
	v_max_f32_e32 v25, v95, v95
	v_max_f32_e32 v95, v25, v24
.LBB0_373:
	s_mov_b64 s[26:27], 0x14000
	v_lshl_add_u64 v[24:25], v[32:33], 0, s[26:27]
	global_store_dwordx4 v[24:25], v[20:23], off offset:256
	s_and_b64 vcc, exec, s[12:13]
	s_nop 0
	v_mov_b32_e32 v21, v12
	v_mov_b32_e32 v12, v17
	v_mov_b32_e32 v20, v16
	v_pk_mul_f32 v[16:17], v[12:13], v[96:97]
	s_nop 0
	v_pk_fma_f32 v[16:17], v[20:21], v[92:93], v[16:17] neg_lo:[0,0,1] neg_hi:[0,0,1]
	v_pk_mul_f32 v[20:21], v[20:21], v[96:97]
	s_nop 0
	v_pk_fma_f32 v[20:21], v[12:13], v[92:93], v[20:21]
	v_mov_b32_e32 v13, v14
	v_mov_b32_e32 v14, v19
	v_mov_b32_e32 v12, v18
	v_pk_mul_f32 v[18:19], v[14:15], v[158:159]
	s_nop 0
	v_pk_fma_f32 v[18:19], v[12:13], v[122:123], v[18:19] neg_lo:[0,0,1] neg_hi:[0,0,1]
	v_pk_mul_f32 v[12:13], v[12:13], v[158:159]
	s_nop 0
	v_pk_fma_f32 v[22:23], v[14:15], v[122:123], v[12:13]
	v_mul_f32_e32 v12, v186, v16
	v_mul_f32_e32 v13, v186, v20
	v_cvt_pk_bf16_f32 v12, v12, v13
	v_mul_f32_e32 v13, v186, v18
	v_mul_f32_e32 v14, v186, v22
	v_cvt_pk_bf16_f32 v13, v13, v14
	v_mul_f32_e32 v14, v186, v17
	v_mul_f32_e32 v15, v186, v21
	v_cvt_pk_bf16_f32 v14, v14, v15
	v_mul_f32_e32 v15, v186, v19
	v_mul_f32_e32 v24, v186, v23
	v_cvt_pk_bf16_f32 v15, v15, v24
	s_cbranch_vccnz .LBB0_375
	v_pk_mul_f32 v[20:21], v[20:21], v[20:21]
	v_pk_mul_f32 v[22:23], v[22:23], v[22:23]
	v_pk_fma_f32 v[16:17], v[16:17], v[16:17], v[20:21]
	v_pk_fma_f32 v[18:19], v[18:19], v[18:19], v[22:23]
	s_nop 0
	v_pk_add_f32 v[16:17], v[16:17], v[18:19]
	s_nop 0
	v_add_f32_e32 v16, v16, v17
	v_mov_b32_e32 v17, v16
	s_nop 1
	v_permlane16_swap_b32_e32 v16, v17
	s_waitcnt lgkmcnt(0)
	v_add_f32_e32 v16, v16, v17
	v_mov_b32_e32 v17, v16
	s_nop 1
	v_permlane32_swap_b32_e32 v16, v17
	v_add_f32_e32 v16, v16, v17
	v_max_f32_e32 v17, v94, v94
	v_max_f32_e32 v94, v17, v16

.LBB0_647:
	v_readlane_b32 s5, v254, 35
	s_waitcnt lgkmcnt(0)
	s_add_u32 s5, s22, s5
	s_addc_u32 s19, s23, 0
	s_add_u32 s5, s5, 0x100000
	s_addc_u32 s49, s19, 0
	s_lshr_b32 s19, s72, 14
	s_add_i32 s19, s19, 8
	s_ashr_i32 s29, s18, 4
	s_and_b64 s[54:55], s[54:55], exec
	s_cselect_b32 s19, s19, s29
	s_lshl_b32 s29, s28, 8
	s_mul_hi_i32 s55, s19, 0x4800
	s_mul_i32 s54, s19, 0x4800
	s_or_b32 s63, s29, s51
	s_lshl_b64 s[54:55], s[54:55], 2
	v_or_b32_e32 v132, s63, v179
	s_add_u32 s66, s5, s54
	s_addc_u32 s67, s49, s55
	v_ashrrev_i32_e32 v133, 31, v132
	v_lshl_add_u64 v[132:133], v[132:133], 2, s[66:67]
	s_mov_b32 s19, 0xa000
	s_mov_b64 s[66:67], 0xa000
	v_add_co_u32_e32 v142, vcc, s19, v132
	v_lshl_add_u64 v[140:141], v[132:133], 0, s[66:67]
	s_nop 0
	v_addc_co_u32_e32 v143, vcc, 0, v133, vcc
	global_load_dwordx4 v[132:135], v[140:141], off offset:64
	global_load_dwordx4 v[136:139], v[140:141], off offset:512
	s_nop 0
	global_load_dwordx4 v[142:145], v[142:143], off
	s_nop 0
	global_load_dwordx4 v[154:157], v[140:141], off offset:576
	v_or3_b32 v140, v183, s51, v181
	v_add_u32_e32 v140, s29, v140
	v_ashrrev_i32_e32 v141, 31, v140
	v_lshl_add_u64 v[152:153], v[140:141], 2, s[60:61]
	v_readlane_b32 s60, v254, 54
	v_lshl_add_u64 v[140:141], v[152:153], 0, s[6:7]
	v_readlane_b32 s61, v254, 55
	global_load_dwordx4 v[146:149], v[140:141], off nt
	global_load_dwordx4 v[158:161], v[140:141], off offset:512 nt
	v_lshl_add_u64 v[140:141], v[152:153], 0, s[60:61]
	v_readlane_b32 s60, v254, 58
	global_load_dwordx4 v[174:177], v[140:141], off nt
	global_load_dwordx4 v[190:193], v[140:141], off offset:512 nt
	v_lshl_add_u64 v[140:141], v[152:153], 0, s[34:35]
	v_readlane_b32 s61, v254, 59
	global_load_dwordx4 v[194:197], v[140:141], off nt
	global_load_dwordx4 v[198:201], v[140:141], off offset:512 nt
	v_lshl_add_u64 v[140:141], v[152:153], 0, s[60:61]
	v_readlane_b32 s60, v254, 62
	global_load_dwordx4 v[202:205], v[140:141], off nt
	global_load_dwordx4 v[214:217], v[140:141], off offset:512 nt
	v_lshl_add_u64 v[140:141], v[152:153], 0, s[40:41]
	v_readlane_b32 s61, v254, 63
	global_load_dwordx4 v[218:221], v[140:141], off nt
	global_load_dwordx4 v[222:225], v[140:141], off offset:512 nt
	v_lshl_add_u64 v[140:141], v[152:153], 0, s[60:61]
	v_readlane_b32 s60, v255, 2
	global_load_dwordx4 v[226:229], v[140:141], off nt
	global_load_dwordx4 v[230:233], v[140:141], off offset:512 nt
	v_lshl_add_u64 v[140:141], v[152:153], 0, s[46:47]
	v_readlane_b32 s61, v255, 3
	global_load_dwordx4 v[234:237], v[140:141], off nt
	global_load_dwordx4 v[238:241], v[140:141], off offset:512 nt
	v_lshl_add_u64 v[140:141], v[152:153], 0, s[60:61]
	global_load_dwordx4 v[250:253], v[140:141], off nt
	global_load_dwordx4 v[206:209], v[140:141], off offset:512 nt
	s_waitcnt vmcnt(0)
	ds_write_b128 v182, v[146:149]
	ds_write_b128 v182, v[174:177] offset:1152
	ds_read_b128 v[146:149], v180
	ds_read_b128 v[174:177], v180 offset:64
	ds_write_b128 v182, v[158:161]
	ds_write_b128 v182, v[190:193] offset:1152
	ds_read_b128 v[158:161], v180
	ds_read_b128 v[190:193], v180 offset:64
	s_waitcnt lgkmcnt(5)
	v_pk_mul_f32 v[146:147], v[146:147], s[80:81] op_sel_hi:[1,0]
	v_pk_add_f32 v[142:143], v[142:143], 1.0 op_sel_hi:[1,0]
	ds_write_b128 v182, v[194:197]
	ds_write_b128 v182, v[202:205] offset:1152
	v_pk_add_f32 v[140:141], v[144:145], 1.0 op_sel_hi:[1,0]
	v_pk_fma_f32 v[128:129], v[128:129], v[142:143], v[146:147]
	s_waitcnt lgkmcnt(6)
	v_pk_mul_f32 v[144:145], v[176:177], s[80:81] op_sel_hi:[1,0]
	v_pk_mul_f32 v[146:147], v[174:175], s[80:81] op_sel_hi:[1,0]
	ds_read_b128 v[174:177], v180
	ds_read_b128 v[194:197], v180 offset:64
	v_pk_mul_f32 v[148:149], v[148:149], s[80:81] op_sel_hi:[1,0]
	v_pk_add_f32 v[150:151], v[132:133], 1.0 op_sel_hi:[1,0]
	v_pk_fma_f32 v[130:131], v[130:131], v[140:141], v[148:149]
	v_pk_add_f32 v[148:149], v[134:135], 1.0 op_sel_hi:[1,0]
	v_pk_fma_f32 v[132:133], v[124:125], v[150:151], v[146:147]
	v_pk_fma_f32 v[134:135], v[126:127], v[148:149], v[144:145]
	s_waitcnt lgkmcnt(5)
	v_pk_mul_f32 v[144:145], v[160:161], s[80:81] op_sel_hi:[1,0]
	v_pk_add_f32 v[124:125], v[138:139], 1.0 op_sel_hi:[1,0]
	ds_write_b128 v182, v[198:201]
	ds_write_b128 v182, v[214:217] offset:1152
	v_pk_mul_f32 v[146:147], v[158:159], s[80:81] op_sel_hi:[1,0]
	v_pk_fma_f32 v[138:139], v[122:123], v[124:125], v[144:145]
	s_waitcnt lgkmcnt(6)
	v_pk_mul_f32 v[144:145], v[192:193], s[80:81] op_sel_hi:[1,0]
	v_pk_mul_f32 v[162:163], v[190:191], s[80:81] op_sel_hi:[1,0]
	ds_read_b128 v[158:161], v180
	ds_read_b128 v[190:193], v180 offset:64
	v_pk_add_f32 v[126:127], v[136:137], 1.0 op_sel_hi:[1,0]
	v_pk_add_f32 v[122:123], v[154:155], 1.0 op_sel_hi:[1,0]
	v_pk_fma_f32 v[136:137], v[120:121], v[126:127], v[146:147]
	v_pk_add_f32 v[120:121], v[156:157], 1.0 op_sel_hi:[1,0]
	s_nop 0
	v_pk_fma_f32 v[146:147], v[106:107], v[120:121], v[144:145]
	v_pk_fma_f32 v[144:145], v[104:105], v[122:123], v[162:163]
	s_waitcnt lgkmcnt(5)
	v_pk_mul_f32 v[104:105], v[176:177], s[80:81] op_sel_hi:[1,0]
	v_pk_mul_f32 v[106:107], v[174:175], s[80:81] op_sel_hi:[1,0]
	v_pk_fma_f32 v[110:111], v[110:111], v[140:141], v[104:105]
	v_pk_fma_f32 v[108:109], v[108:109], v[142:143], v[106:107]
	s_waitcnt lgkmcnt(4)
	v_pk_mul_f32 v[104:105], v[196:197], s[80:81] op_sel_hi:[1,0]
	v_pk_mul_f32 v[106:107], v[194:195], s[80:81] op_sel_hi:[1,0]
	v_pk_fma_f32 v[118:119], v[118:119], v[148:149], v[104:105]
	v_pk_fma_f32 v[116:117], v[116:117], v[150:151], v[106:107]
	s_waitcnt lgkmcnt(1)
	v_pk_mul_f32 v[104:105], v[160:161], s[80:81] op_sel_hi:[1,0]
	v_pk_mul_f32 v[106:107], v[158:159], s[80:81] op_sel_hi:[1,0]
	v_pk_fma_f32 v[102:103], v[102:103], v[124:125], v[104:105]
	s_waitcnt lgkmcnt(0)
	v_pk_mul_f32 v[104:105], v[192:193], s[80:81] op_sel_hi:[1,0]
	v_pk_mul_f32 v[154:155], v[190:191], s[80:81] op_sel_hi:[1,0]
	v_pk_fma_f32 v[100:101], v[100:101], v[126:127], v[106:107]
	v_pk_fma_f32 v[106:107], v[98:99], v[120:121], v[104:105]
	v_pk_fma_f32 v[104:105], v[96:97], v[122:123], v[154:155]
	v_readlane_b32 s60, v255, 6
	v_lshl_add_u64 v[96:97], v[152:153], 0, s[52:53]
	v_readlane_b32 s61, v255, 7
	global_load_dwordx4 v[154:157], v[96:97], off nt
	global_load_dwordx4 v[158:161], v[96:97], off offset:512 nt
	v_lshl_add_u64 v[96:97], v[152:153], 0, s[60:61]
	v_readlane_b32 s60, v255, 12
	global_load_dwordx4 v[174:177], v[96:97], off nt
	global_load_dwordx4 v[190:193], v[96:97], off offset:512 nt
	v_lshl_add_u64 v[96:97], v[152:153], 0, s[58:59]
	v_readlane_b32 s61, v255, 13
	global_load_dwordx4 v[194:197], v[96:97], off nt
	global_load_dwordx4 v[198:201], v[96:97], off offset:512 nt
	v_lshl_add_u64 v[96:97], v[152:153], 0, s[60:61]
	global_load_dwordx4 v[202:205], v[96:97], off nt
	global_load_dwordx4 v[214:217], v[96:97], off offset:512 nt
	ds_write_b128 v182, v[218:221]
	ds_write_b128 v182, v[226:229] offset:1152
	ds_read_b128 v[96:99], v180
	ds_read_b128 v[218:221], v180 offset:64
	ds_write_b128 v182, v[222:225]
	ds_write_b128 v182, v[230:233] offset:1152
	ds_read_b128 v[222:225], v180
	ds_read_b128 v[226:229], v180 offset:64
	ds_write_b128 v182, v[234:237]
	ds_write_b128 v182, v[250:253] offset:1152
	ds_read_b128 v[230:233], v180
	ds_read_b128 v[234:237], v180 offset:64
	s_waitcnt lgkmcnt(9)
	v_pk_mul_f32 v[96:97], v[96:97], s[80:81] op_sel_hi:[1,0]
	v_pk_mul_f32 v[98:99], v[98:99], s[80:81] op_sel_hi:[1,0]
	v_pk_fma_f32 v[92:93], v[92:93], v[142:143], v[96:97]
	s_waitcnt lgkmcnt(8)
	v_pk_mul_f32 v[96:97], v[220:221], s[80:81] op_sel_hi:[1,0]
	v_pk_mul_f32 v[162:163], v[218:219], s[80:81] op_sel_hi:[1,0]
	v_pk_fma_f32 v[94:95], v[94:95], v[140:141], v[98:99]
	v_pk_fma_f32 v[98:99], v[90:91], v[148:149], v[96:97]
	v_pk_fma_f32 v[96:97], v[88:89], v[150:151], v[162:163]
	ds_write_b128 v182, v[238:241]
	ds_write_b128 v182, v[206:209] offset:1152
	ds_read_b128 v[206:209], v180
	ds_read_b128 v[218:221], v180 offset:64
	s_waitcnt lgkmcnt(9)
	v_pk_mul_f32 v[88:89], v[224:225], s[80:81] op_sel_hi:[1,0]
	v_pk_mul_f32 v[90:91], v[222:223], s[80:81] op_sel_hi:[1,0]
	v_pk_fma_f32 v[86:87], v[86:87], v[124:125], v[88:89]
	s_waitcnt lgkmcnt(8)
	v_pk_mul_f32 v[88:89], v[228:229], s[80:81] op_sel_hi:[1,0]
	v_pk_mul_f32 v[162:163], v[226:227], s[80:81] op_sel_hi:[1,0]
	v_pk_fma_f32 v[84:85], v[84:85], v[126:127], v[90:91]
	v_pk_fma_f32 v[90:91], v[74:75], v[120:121], v[88:89]
	v_pk_fma_f32 v[88:89], v[72:73], v[122:123], v[162:163]
	s_waitcnt lgkmcnt(5)
	v_pk_mul_f32 v[72:73], v[232:233], s[80:81] op_sel_hi:[1,0]
	v_pk_mul_f32 v[74:75], v[230:231], s[80:81] op_sel_hi:[1,0]
	v_pk_fma_f32 v[78:79], v[78:79], v[140:141], v[72:73]
	v_pk_fma_f32 v[76:77], v[76:77], v[142:143], v[74:75]
	s_waitcnt lgkmcnt(4)
	v_pk_mul_f32 v[72:73], v[236:237], s[80:81] op_sel_hi:[1,0]
	v_pk_mul_f32 v[74:75], v[234:235], s[80:81] op_sel_hi:[1,0]
	v_pk_fma_f32 v[82:83], v[82:83], v[148:149], v[72:73]
	v_pk_fma_f32 v[80:81], v[80:81], v[150:151], v[74:75]
	s_waitcnt lgkmcnt(1)
	v_pk_mul_f32 v[72:73], v[208:209], s[80:81] op_sel_hi:[1,0]
	v_pk_mul_f32 v[74:75], v[206:207], s[80:81] op_sel_hi:[1,0]
	v_pk_fma_f32 v[70:71], v[70:71], v[124:125], v[72:73]
	s_waitcnt lgkmcnt(0)
	v_pk_mul_f32 v[72:73], v[220:221], s[80:81] op_sel_hi:[1,0]
	v_pk_mul_f32 v[162:163], v[218:219], s[80:81] op_sel_hi:[1,0]
	v_pk_fma_f32 v[68:69], v[68:69], v[126:127], v[74:75]
	v_pk_fma_f32 v[74:75], v[66:67], v[120:121], v[72:73]
	v_pk_fma_f32 v[72:73], v[64:65], v[122:123], v[162:163]
	v_readlane_b32 s60, v254, 40
	v_lshl_add_u64 v[64:65], v[152:153], 0, s[64:65]
	v_readlane_b32 s61, v254, 41
	global_load_dwordx4 v[206:209], v[64:65], off nt
	global_load_dwordx4 v[218:221], v[64:65], off offset:512 nt
	v_lshl_add_u64 v[64:65], v[152:153], 0, s[60:61]
	v_readlane_b32 s60, v254, 42
	global_load_dwordx4 v[222:225], v[64:65], off nt
	global_load_dwordx4 v[226:229], v[64:65], off offset:512 nt
	v_lshl_add_u64 v[64:65], v[152:153], 0, s[78:79]
	v_readlane_b32 s61, v254, 43
	global_load_dwordx4 v[230:233], v[64:65], off nt
	global_load_dwordx4 v[234:237], v[64:65], off offset:512 nt
	v_lshl_add_u64 v[64:65], v[152:153], 0, s[60:61]
	global_load_dwordx4 v[238:241], v[64:65], off nt
	global_load_dwordx4 v[250:253], v[64:65], off offset:512 nt
	s_waitcnt vmcnt(15)
	ds_write_b128 v182, v[154:157]
	s_waitcnt vmcnt(13)
	ds_write_b128 v182, v[174:177] offset:1152
	ds_read_b128 v[64:67], v180
	ds_read_b128 v[152:155], v180 offset:64
	ds_write_b128 v182, v[158:161]
	s_waitcnt vmcnt(12)
	ds_write_b128 v182, v[190:193] offset:1152
	ds_read_b128 v[156:159], v180
	ds_read_b128 v[160:163], v180 offset:64
	s_waitcnt vmcnt(11)
	ds_write_b128 v182, v[194:197]
	s_waitcnt vmcnt(9)
	ds_write_b128 v182, v[202:205] offset:1152
	ds_read_b128 v[174:177], v180
	ds_read_b128 v[190:193], v180 offset:64
	s_waitcnt lgkmcnt(9)
	v_pk_mul_f32 v[64:65], v[64:65], s[80:81] op_sel_hi:[1,0]
	v_pk_mul_f32 v[66:67], v[66:67], s[80:81] op_sel_hi:[1,0]
	v_pk_fma_f32 v[60:61], v[60:61], v[142:143], v[64:65]
	s_waitcnt lgkmcnt(8)
	v_pk_mul_f32 v[64:65], v[154:155], s[80:81] op_sel_hi:[1,0]
	v_pk_mul_f32 v[152:153], v[152:153], s[80:81] op_sel_hi:[1,0]
	v_pk_fma_f32 v[62:63], v[62:63], v[140:141], v[66:67]
	v_pk_fma_f32 v[66:67], v[58:59], v[148:149], v[64:65]
	v_pk_fma_f32 v[64:65], v[56:57], v[150:151], v[152:153]
	ds_write_b128 v182, v[198:201]
	s_waitcnt vmcnt(8)
	ds_write_b128 v182, v[214:217] offset:1152
	s_waitcnt lgkmcnt(7)
	v_pk_mul_f32 v[56:57], v[158:159], s[80:81] op_sel_hi:[1,0]
	v_pk_mul_f32 v[58:59], v[156:157], s[80:81] op_sel_hi:[1,0]
	ds_read_b128 v[152:155], v180
	ds_read_b128 v[156:159], v180 offset:64
	v_pk_fma_f32 v[54:55], v[54:55], v[124:125], v[56:57]
	s_waitcnt lgkmcnt(8)
	v_pk_mul_f32 v[56:57], v[162:163], s[80:81] op_sel_hi:[1,0]
	v_pk_mul_f32 v[160:161], v[160:161], s[80:81] op_sel_hi:[1,0]
	v_pk_fma_f32 v[52:53], v[52:53], v[126:127], v[58:59]
	v_pk_fma_f32 v[58:59], v[42:43], v[120:121], v[56:57]
	v_pk_fma_f32 v[56:57], v[40:41], v[122:123], v[160:161]
	s_waitcnt lgkmcnt(5)
	v_pk_mul_f32 v[40:41], v[176:177], s[80:81] op_sel_hi:[1,0]
	v_pk_mul_f32 v[42:43], v[174:175], s[80:81] op_sel_hi:[1,0]
	v_pk_fma_f32 v[46:47], v[46:47], v[140:141], v[40:41]
	v_pk_fma_f32 v[44:45], v[44:45], v[142:143], v[42:43]
	s_waitcnt lgkmcnt(4)
	v_pk_mul_f32 v[40:41], v[192:193], s[80:81] op_sel_hi:[1,0]
	v_pk_mul_f32 v[42:43], v[190:191], s[80:81] op_sel_hi:[1,0]
	v_pk_fma_f32 v[50:51], v[50:51], v[148:149], v[40:41]
	v_pk_fma_f32 v[48:49], v[48:49], v[150:151], v[42:43]
	s_waitcnt lgkmcnt(1)
	v_pk_mul_f32 v[40:41], v[154:155], s[80:81] op_sel_hi:[1,0]
	v_pk_mul_f32 v[42:43], v[152:153], s[80:81] op_sel_hi:[1,0]
	v_pk_fma_f32 v[38:39], v[38:39], v[124:125], v[40:41]
	s_waitcnt lgkmcnt(0)
	v_pk_mul_f32 v[40:41], v[158:159], s[80:81] op_sel_hi:[1,0]
	v_pk_mul_f32 v[152:153], v[156:157], s[80:81] op_sel_hi:[1,0]
	v_pk_fma_f32 v[36:37], v[36:37], v[126:127], v[42:43]
	v_pk_fma_f32 v[42:43], v[34:35], v[120:121], v[40:41]
	v_pk_fma_f32 v[40:41], v[32:33], v[122:123], v[152:153]
	s_nop 0
	s_waitcnt vmcnt(7)
	ds_write_b128 v182, v[206:209]
	s_waitcnt vmcnt(5)
	ds_write_b128 v182, v[222:225] offset:1152
	ds_read_b128 v[32:35], v180
	ds_read_b128 v[152:155], v180 offset:64
	ds_write_b128 v182, v[218:221]
	s_waitcnt vmcnt(4)
	ds_write_b128 v182, v[226:229] offset:1152
	ds_read_b128 v[156:159], v180
	ds_read_b128 v[160:163], v180 offset:64
	s_waitcnt vmcnt(3)
	ds_write_b128 v182, v[230:233]
	s_waitcnt vmcnt(1)
	ds_write_b128 v182, v[238:241] offset:1152
	ds_read_b128 v[174:177], v180
	ds_read_b128 v[190:193], v180 offset:64
	s_waitcnt lgkmcnt(9)
	v_pk_mul_f32 v[32:33], v[32:33], s[80:81] op_sel_hi:[1,0]
	v_pk_mul_f32 v[34:35], v[34:35], s[80:81] op_sel_hi:[1,0]
	v_pk_fma_f32 v[28:29], v[28:29], v[142:143], v[32:33]
	s_waitcnt lgkmcnt(8)
	v_pk_mul_f32 v[32:33], v[154:155], s[80:81] op_sel_hi:[1,0]
	v_pk_mul_f32 v[152:153], v[152:153], s[80:81] op_sel_hi:[1,0]
	v_pk_fma_f32 v[30:31], v[30:31], v[140:141], v[34:35]
	v_pk_fma_f32 v[34:35], v[26:27], v[148:149], v[32:33]
	v_pk_fma_f32 v[32:33], v[24:25], v[150:151], v[152:153]
	ds_write_b128 v182, v[234:237]
	s_waitcnt vmcnt(0)
	ds_write_b128 v182, v[250:253] offset:1152
	s_waitcnt lgkmcnt(7)
	v_pk_mul_f32 v[24:25], v[158:159], s[80:81] op_sel_hi:[1,0]
	v_pk_mul_f32 v[26:27], v[156:157], s[80:81] op_sel_hi:[1,0]
	ds_read_b128 v[152:155], v180
	ds_read_b128 v[156:159], v180 offset:64
	v_pk_fma_f32 v[22:23], v[22:23], v[124:125], v[24:25]
	s_waitcnt lgkmcnt(8)
	v_pk_mul_f32 v[24:25], v[162:163], s[80:81] op_sel_hi:[1,0]
	v_pk_mul_f32 v[160:161], v[160:161], s[80:81] op_sel_hi:[1,0]
	v_pk_fma_f32 v[20:21], v[20:21], v[126:127], v[26:27]
	v_pk_fma_f32 v[26:27], v[14:15], v[120:121], v[24:25]
	v_pk_fma_f32 v[24:25], v[12:13], v[122:123], v[160:161]
	s_waitcnt lgkmcnt(5)
	v_pk_mul_f32 v[12:13], v[176:177], s[80:81] op_sel_hi:[1,0]
	v_pk_mul_f32 v[160:161], v[174:175], s[80:81] op_sel_hi:[1,0]
	v_pk_fma_f32 v[14:15], v[114:115], v[140:141], v[12:13]
	v_pk_fma_f32 v[12:13], v[112:113], v[142:143], v[160:161]
	s_waitcnt lgkmcnt(4)
	v_pk_mul_f32 v[112:113], v[192:193], s[80:81] op_sel_hi:[1,0]
	v_pk_mul_f32 v[114:115], v[190:191], s[80:81] op_sel_hi:[1,0]
	v_pk_fma_f32 v[18:19], v[18:19], v[148:149], v[112:113]
	v_pk_fma_f32 v[16:17], v[16:17], v[150:151], v[114:115]
	s_waitcnt lgkmcnt(1)
	v_pk_mul_f32 v[112:113], v[154:155], s[80:81] op_sel_hi:[1,0]
	v_pk_mul_f32 v[114:115], v[152:153], s[80:81] op_sel_hi:[1,0]
	v_pk_fma_f32 v[6:7], v[6:7], v[124:125], v[112:113]
	s_waitcnt lgkmcnt(0)
	v_pk_mul_f32 v[112:113], v[158:159], s[80:81] op_sel_hi:[1,0]
	v_pk_fma_f32 v[4:5], v[4:5], v[126:127], v[114:115]
	v_pk_mul_f32 v[114:115], v[156:157], s[80:81] op_sel_hi:[1,0]
	v_pk_fma_f32 v[10:11], v[10:11], v[120:121], v[112:113]
	v_add_f32_e32 v112, v128, v129
	v_add_f32_e32 v113, v130, v131
	v_pk_fma_f32 v[8:9], v[8:9], v[122:123], v[114:115]
	v_add_f32_e32 v112, v112, v113
	v_mul_f32_e32 v113, v129, v129
	v_mul_f32_e32 v114, v131, v131
	v_fmac_f32_e32 v113, v128, v128
	v_fmac_f32_e32 v114, v130, v130
	v_add_f32_e32 v113, v113, v114
	v_add_f32_e32 v114, v132, v133
	v_add_f32_e32 v115, v134, v135
	v_add_f32_e32 v112, 0, v112
	v_add_f32_e32 v114, v114, v115
	v_add_f32_e32 v112, v114, v112
	v_mul_f32_e32 v114, v133, v133
	v_mul_f32_e32 v115, v135, v135
	v_fmac_f32_e32 v114, v132, v132
	v_fmac_f32_e32 v115, v134, v134
	v_add_f32_e32 v114, v114, v115
	v_add_f32_e32 v113, v113, v114
	v_add_f32_e32 v114, v136, v137
	v_add_f32_e32 v115, v138, v139
	v_add_f32_e32 v114, v114, v115
	v_add_f32_e32 v112, v114, v112
	v_mul_f32_e32 v114, v137, v137
	v_mul_f32_e32 v115, v139, v139
	v_fmac_f32_e32 v114, v136, v136
	v_fmac_f32_e32 v115, v138, v138
	v_add_f32_e32 v114, v114, v115
	v_add_f32_e32 v113, v114, v113
	v_add_f32_e32 v114, v144, v145
	v_add_f32_e32 v115, v146, v147
	v_add_f32_e32 v114, v114, v115
	v_add_f32_e32 v112, v114, v112
	v_mul_f32_e32 v114, v145, v145
	v_mul_f32_e32 v115, v147, v147
	v_fmac_f32_e32 v114, v144, v144
	v_fmac_f32_e32 v115, v146, v146
	v_add_f32_e32 v114, v114, v115
	v_add_f32_e32 v113, v114, v113
	v_mov_b32_e32 v114, v112
	v_mov_b32_e32 v115, v113
	s_nop 0
	v_permlane16_swap_b32_e32 v112, v114
	v_permlane16_swap_b32_e32 v113, v115
	v_add_f32_e32 v112, v112, v114
	v_add_f32_e32 v113, v113, v115
	v_mov_b32_e32 v114, v112
	v_mov_b32_e32 v115, v113
	s_nop 0
	v_permlane32_swap_b32_e32 v112, v114
	v_permlane32_swap_b32_e32 v113, v115
	s_and_saveexec_b64 s[60:61], s[8:9]
	v_pk_add_f32 v[112:113], v[112:113], v[114:115]
	ds_write_b64 v188, v[112:113]
	s_or_b64 exec, exec, s[60:61]
	v_add_f32_e32 v112, v108, v109
	v_add_f32_e32 v113, v110, v111
	v_add_f32_e32 v112, v112, v113
	v_mul_f32_e32 v113, v109, v109
	v_mul_f32_e32 v114, v111, v111
	v_fmac_f32_e32 v113, v108, v108
	v_fmac_f32_e32 v114, v110, v110
	v_add_f32_e32 v113, v113, v114
	v_add_f32_e32 v114, v116, v117
	v_add_f32_e32 v115, v118, v119
	v_add_f32_e32 v112, 0, v112
	v_add_f32_e32 v114, v114, v115
	v_add_f32_e32 v112, v114, v112
	v_mul_f32_e32 v114, v117, v117
	v_mul_f32_e32 v115, v119, v119
	v_fmac_f32_e32 v114, v116, v116
	v_fmac_f32_e32 v115, v118, v118
	v_add_f32_e32 v114, v114, v115
	v_add_f32_e32 v113, v113, v114
	v_add_f32_e32 v114, v100, v101
	v_add_f32_e32 v115, v102, v103
	v_add_f32_e32 v114, v114, v115
	v_add_f32_e32 v112, v114, v112
	v_mul_f32_e32 v114, v101, v101
	v_mul_f32_e32 v115, v103, v103
	v_fmac_f32_e32 v114, v100, v100
	v_fmac_f32_e32 v115, v102, v102
	v_add_f32_e32 v114, v114, v115
	v_add_f32_e32 v113, v114, v113
	v_add_f32_e32 v114, v104, v105
	v_add_f32_e32 v115, v106, v107
	v_add_f32_e32 v114, v114, v115
	v_add_f32_e32 v112, v114, v112
	v_mul_f32_e32 v114, v105, v105
	v_mul_f32_e32 v115, v107, v107
	v_fmac_f32_e32 v114, v104, v104
	v_fmac_f32_e32 v115, v106, v106
	v_add_f32_e32 v114, v114, v115
	v_add_f32_e32 v113, v114, v113
	v_mov_b32_e32 v114, v112
	v_mov_b32_e32 v115, v113
	s_nop 0
	v_permlane16_swap_b32_e32 v112, v114
	v_permlane16_swap_b32_e32 v113, v115
	v_add_f32_e32 v112, v112, v114
	v_add_f32_e32 v113, v113, v115
	v_mov_b32_e32 v114, v112
	v_mov_b32_e32 v115, v113
	s_nop 0
	v_permlane32_swap_b32_e32 v112, v114
	v_permlane32_swap_b32_e32 v113, v115
	s_and_saveexec_b64 s[60:61], s[8:9]
	v_pk_add_f32 v[112:113], v[112:113], v[114:115]
	ds_write_b64 v188, v[112:113] offset:512
	s_or_b64 exec, exec, s[60:61]
	v_add_f32_e32 v112, v92, v93
	v_add_f32_e32 v113, v94, v95
	v_add_f32_e32 v112, v112, v113
	v_mul_f32_e32 v113, v93, v93
	v_mul_f32_e32 v114, v95, v95
	v_fmac_f32_e32 v113, v92, v92
	v_fmac_f32_e32 v114, v94, v94
	v_add_f32_e32 v113, v113, v114
	v_add_f32_e32 v114, v96, v97
	v_add_f32_e32 v115, v98, v99
	v_add_f32_e32 v112, 0, v112
	v_add_f32_e32 v114, v114, v115
	v_add_f32_e32 v112, v114, v112
	v_mul_f32_e32 v114, v97, v97
	v_mul_f32_e32 v115, v99, v99
	v_fmac_f32_e32 v114, v96, v96
	v_fmac_f32_e32 v115, v98, v98
	v_add_f32_e32 v114, v114, v115
	v_add_f32_e32 v113, v113, v114
	v_add_f32_e32 v114, v84, v85
	v_add_f32_e32 v115, v86, v87
	v_add_f32_e32 v114, v114, v115
	v_add_f32_e32 v112, v114, v112
	v_mul_f32_e32 v114, v85, v85
	v_mul_f32_e32 v115, v87, v87
	v_fmac_f32_e32 v114, v84, v84
	v_fmac_f32_e32 v115, v86, v86
	v_add_f32_e32 v114, v114, v115
	v_add_f32_e32 v113, v114, v113
	v_add_f32_e32 v114, v88, v89
	v_add_f32_e32 v115, v90, v91
	v_add_f32_e32 v114, v114, v115
	v_add_f32_e32 v112, v114, v112
	v_mul_f32_e32 v114, v89, v89
	v_mul_f32_e32 v115, v91, v91
	v_fmac_f32_e32 v114, v88, v88
	v_fmac_f32_e32 v115, v90, v90
	v_add_f32_e32 v114, v114, v115
	v_add_f32_e32 v113, v114, v113
	v_mov_b32_e32 v114, v112
	v_mov_b32_e32 v115, v113
	s_nop 0
	v_permlane16_swap_b32_e32 v112, v114
	v_permlane16_swap_b32_e32 v113, v115
	v_add_f32_e32 v112, v112, v114
	v_add_f32_e32 v113, v113, v115
	v_mov_b32_e32 v114, v112
	v_mov_b32_e32 v115, v113
	s_nop 0
	v_permlane32_swap_b32_e32 v112, v114
	v_permlane32_swap_b32_e32 v113, v115
	s_and_saveexec_b64 s[60:61], s[8:9]
	v_pk_add_f32 v[112:113], v[112:113], v[114:115]
	ds_write_b64 v188, v[112:113] offset:1024
	s_or_b64 exec, exec, s[60:61]
	v_add_f32_e32 v112, v76, v77
	v_add_f32_e32 v113, v78, v79
	v_add_f32_e32 v112, v112, v113
	v_mul_f32_e32 v113, v77, v77
	v_mul_f32_e32 v114, v79, v79
	v_fmac_f32_e32 v113, v76, v76
	v_fmac_f32_e32 v114, v78, v78
	v_add_f32_e32 v113, v113, v114
	v_add_f32_e32 v114, v80, v81
	v_add_f32_e32 v115, v82, v83
	v_add_f32_e32 v112, 0, v112
	v_add_f32_e32 v114, v114, v115
	v_add_f32_e32 v112, v114, v112
	v_mul_f32_e32 v114, v81, v81
	v_mul_f32_e32 v115, v83, v83
	v_fmac_f32_e32 v114, v80, v80
	v_fmac_f32_e32 v115, v82, v82
	v_add_f32_e32 v114, v114, v115
	v_add_f32_e32 v113, v113, v114
	v_add_f32_e32 v114, v68, v69
	v_add_f32_e32 v115, v70, v71
	v_add_f32_e32 v114, v114, v115
	v_add_f32_e32 v112, v114, v112
	v_mul_f32_e32 v114, v69, v69
	v_mul_f32_e32 v115, v71, v71
	v_fmac_f32_e32 v114, v68, v68
	v_fmac_f32_e32 v115, v70, v70
	v_add_f32_e32 v114, v114, v115
	v_add_f32_e32 v113, v114, v113
	v_add_f32_e32 v114, v72, v73
	v_add_f32_e32 v115, v74, v75
	v_add_f32_e32 v114, v114, v115
	v_add_f32_e32 v112, v114, v112
	v_mul_f32_e32 v114, v73, v73
	v_mul_f32_e32 v115, v75, v75
	v_fmac_f32_e32 v114, v72, v72
	v_fmac_f32_e32 v115, v74, v74
	v_add_f32_e32 v114, v114, v115
	v_add_f32_e32 v113, v114, v113
	v_mov_b32_e32 v114, v112
	v_mov_b32_e32 v115, v113
	s_nop 0
	v_permlane16_swap_b32_e32 v112, v114
	v_permlane16_swap_b32_e32 v113, v115
	v_add_f32_e32 v112, v112, v114
	v_add_f32_e32 v113, v113, v115
	v_mov_b32_e32 v114, v112
	v_mov_b32_e32 v115, v113
	s_nop 0
	v_permlane32_swap_b32_e32 v112, v114
	v_permlane32_swap_b32_e32 v113, v115
	s_and_saveexec_b64 s[60:61], s[8:9]
	v_pk_add_f32 v[112:113], v[112:113], v[114:115]
	ds_write_b64 v188, v[112:113] offset:1536
	s_or_b64 exec, exec, s[60:61]
	v_add_f32_e32 v112, v60, v61
	v_add_f32_e32 v113, v62, v63
	v_add_f32_e32 v112, v112, v113
	v_mul_f32_e32 v113, v61, v61
	v_mul_f32_e32 v114, v63, v63
	v_fmac_f32_e32 v113, v60, v60
	v_fmac_f32_e32 v114, v62, v62
	v_add_f32_e32 v113, v113, v114
	v_add_f32_e32 v114, v64, v65
	v_add_f32_e32 v115, v66, v67
	v_add_f32_e32 v112, 0, v112
	v_add_f32_e32 v114, v114, v115
	v_add_f32_e32 v112, v114, v112
	v_mul_f32_e32 v114, v65, v65
	v_mul_f32_e32 v115, v67, v67
	v_fmac_f32_e32 v114, v64, v64
	v_fmac_f32_e32 v115, v66, v66
	v_add_f32_e32 v114, v114, v115
	v_add_f32_e32 v113, v113, v114
	v_add_f32_e32 v114, v52, v53
	v_add_f32_e32 v115, v54, v55
	v_add_f32_e32 v114, v114, v115
	v_add_f32_e32 v112, v114, v112
	v_mul_f32_e32 v114, v53, v53
	v_mul_f32_e32 v115, v55, v55
	v_fmac_f32_e32 v114, v52, v52
	v_fmac_f32_e32 v115, v54, v54
	v_add_f32_e32 v114, v114, v115
	v_add_f32_e32 v113, v114, v113
	v_add_f32_e32 v114, v56, v57
	v_add_f32_e32 v115, v58, v59
	v_add_f32_e32 v114, v114, v115
	v_add_f32_e32 v112, v114, v112
	v_mul_f32_e32 v114, v57, v57
	v_mul_f32_e32 v115, v59, v59
	v_fmac_f32_e32 v114, v56, v56
	v_fmac_f32_e32 v115, v58, v58
	v_add_f32_e32 v114, v114, v115
	v_add_f32_e32 v113, v114, v113
	v_mov_b32_e32 v114, v112
	v_mov_b32_e32 v115, v113
	s_nop 0
	v_permlane16_swap_b32_e32 v112, v114
	v_permlane16_swap_b32_e32 v113, v115
	v_add_f32_e32 v112, v112, v114
	v_add_f32_e32 v113, v113, v115
	v_mov_b32_e32 v114, v112
	v_mov_b32_e32 v115, v113
	s_nop 0
	v_permlane32_swap_b32_e32 v112, v114
	v_permlane32_swap_b32_e32 v113, v115
	s_and_saveexec_b64 s[60:61], s[8:9]
	v_pk_add_f32 v[112:113], v[112:113], v[114:115]
	ds_write_b64 v188, v[112:113] offset:4096
	s_or_b64 exec, exec, s[60:61]
	v_add_f32_e32 v112, v44, v45
	v_add_f32_e32 v113, v46, v47
	v_add_f32_e32 v112, v112, v113
	v_mul_f32_e32 v113, v45, v45
	v_mul_f32_e32 v114, v47, v47
	v_fmac_f32_e32 v113, v44, v44
	v_fmac_f32_e32 v114, v46, v46
	v_add_f32_e32 v113, v113, v114
	v_add_f32_e32 v114, v48, v49
	v_add_f32_e32 v115, v50, v51
	v_add_f32_e32 v112, 0, v112
	v_add_f32_e32 v114, v114, v115
	v_add_f32_e32 v112, v114, v112
	v_mul_f32_e32 v114, v49, v49
	v_mul_f32_e32 v115, v51, v51
	v_fmac_f32_e32 v114, v48, v48
	v_fmac_f32_e32 v115, v50, v50
	v_add_f32_e32 v114, v114, v115
	v_add_f32_e32 v113, v113, v114
	v_add_f32_e32 v114, v36, v37
	v_add_f32_e32 v115, v38, v39
	v_add_f32_e32 v114, v114, v115
	v_add_f32_e32 v112, v114, v112
	v_mul_f32_e32 v114, v37, v37
	v_mul_f32_e32 v115, v39, v39
	v_fmac_f32_e32 v114, v36, v36
	v_fmac_f32_e32 v115, v38, v38
	v_add_f32_e32 v114, v114, v115
	v_add_f32_e32 v113, v114, v113
	v_add_f32_e32 v114, v40, v41
	v_add_f32_e32 v115, v42, v43
	v_add_f32_e32 v114, v114, v115
	v_add_f32_e32 v112, v114, v112
	v_mul_f32_e32 v114, v41, v41
	v_mul_f32_e32 v115, v43, v43
	v_fmac_f32_e32 v114, v40, v40
	v_fmac_f32_e32 v115, v42, v42
	v_add_f32_e32 v114, v114, v115
	v_add_f32_e32 v113, v114, v113
	v_mov_b32_e32 v114, v112
	v_mov_b32_e32 v115, v113
	s_nop 0
	v_permlane16_swap_b32_e32 v112, v114
	v_permlane16_swap_b32_e32 v113, v115
	v_add_f32_e32 v112, v112, v114
	v_add_f32_e32 v113, v113, v115
	v_mov_b32_e32 v114, v112
	v_mov_b32_e32 v115, v113
	s_nop 0
	v_permlane32_swap_b32_e32 v112, v114
	v_permlane32_swap_b32_e32 v113, v115
	s_and_saveexec_b64 s[60:61], s[8:9]
	v_pk_add_f32 v[112:113], v[112:113], v[114:115]
	ds_write_b64 v188, v[112:113] offset:4608
	s_or_b64 exec, exec, s[60:61]
	v_add_f32_e32 v112, v28, v29
	v_add_f32_e32 v113, v30, v31
	v_add_f32_e32 v112, v112, v113
	v_mul_f32_e32 v113, v29, v29
	v_mul_f32_e32 v114, v31, v31
	v_fmac_f32_e32 v113, v28, v28
	v_fmac_f32_e32 v114, v30, v30
	v_add_f32_e32 v113, v113, v114
	v_add_f32_e32 v114, v32, v33
	v_add_f32_e32 v115, v34, v35
	v_add_f32_e32 v112, 0, v112
	v_add_f32_e32 v114, v114, v115
	v_add_f32_e32 v112, v114, v112
	v_mul_f32_e32 v114, v33, v33
	v_mul_f32_e32 v115, v35, v35
	v_fmac_f32_e32 v114, v32, v32
	v_fmac_f32_e32 v115, v34, v34
	v_add_f32_e32 v114, v114, v115
	v_add_f32_e32 v113, v113, v114
	v_add_f32_e32 v114, v20, v21
	v_add_f32_e32 v115, v22, v23
	v_add_f32_e32 v114, v114, v115
	v_add_f32_e32 v112, v114, v112
	v_mul_f32_e32 v114, v21, v21
	v_mul_f32_e32 v115, v23, v23
	v_fmac_f32_e32 v114, v20, v20
	v_fmac_f32_e32 v115, v22, v22
	v_add_f32_e32 v114, v114, v115
	v_add_f32_e32 v113, v114, v113
	v_add_f32_e32 v114, v24, v25
	v_add_f32_e32 v115, v26, v27
	v_add_f32_e32 v114, v114, v115
	v_add_f32_e32 v112, v114, v112
	v_mul_f32_e32 v114, v25, v25
	v_mul_f32_e32 v115, v27, v27
	v_fmac_f32_e32 v114, v24, v24
	v_fmac_f32_e32 v115, v26, v26
	v_add_f32_e32 v114, v114, v115
	v_add_f32_e32 v113, v114, v113
	v_mov_b32_e32 v114, v112
	v_mov_b32_e32 v115, v113
	s_nop 0
	v_permlane16_swap_b32_e32 v112, v114
	v_permlane16_swap_b32_e32 v113, v115
	v_add_f32_e32 v112, v112, v114
	v_add_f32_e32 v113, v113, v115
	v_mov_b32_e32 v114, v112
	v_mov_b32_e32 v115, v113
	s_nop 0
	v_permlane32_swap_b32_e32 v112, v114
	v_permlane32_swap_b32_e32 v113, v115
	s_and_saveexec_b64 s[60:61], s[8:9]
	v_pk_add_f32 v[112:113], v[112:113], v[114:115]
	ds_write_b64 v188, v[112:113] offset:5120
	s_or_b64 exec, exec, s[60:61]
	v_add_f32_e32 v112, v12, v13
	v_add_f32_e32 v113, v14, v15
	v_add_f32_e32 v112, v112, v113
	v_mul_f32_e32 v113, v13, v13
	v_mul_f32_e32 v114, v15, v15
	v_fmac_f32_e32 v113, v12, v12
	v_fmac_f32_e32 v114, v14, v14
	v_add_f32_e32 v113, v113, v114
	v_add_f32_e32 v114, v16, v17
	v_add_f32_e32 v115, v18, v19
	v_add_f32_e32 v112, 0, v112
	v_add_f32_e32 v114, v114, v115
	v_add_f32_e32 v112, v114, v112
	v_mul_f32_e32 v114, v17, v17
	v_mul_f32_e32 v115, v19, v19
	v_fmac_f32_e32 v114, v16, v16
	v_fmac_f32_e32 v115, v18, v18
	v_add_f32_e32 v114, v114, v115
	v_add_f32_e32 v113, v113, v114
	v_add_f32_e32 v114, v4, v5
	v_add_f32_e32 v115, v6, v7
	v_add_f32_e32 v114, v114, v115
	v_add_f32_e32 v112, v114, v112
	v_mul_f32_e32 v114, v5, v5
	v_mul_f32_e32 v115, v7, v7
	v_fmac_f32_e32 v114, v4, v4
	v_fmac_f32_e32 v115, v6, v6
	v_add_f32_e32 v114, v114, v115
	v_add_f32_e32 v113, v114, v113
	v_add_f32_e32 v114, v8, v9
	v_add_f32_e32 v115, v10, v11
	v_add_f32_e32 v114, v114, v115
	v_add_f32_e32 v112, v114, v112
	v_mul_f32_e32 v114, v9, v9
	v_mul_f32_e32 v115, v11, v11
	v_fmac_f32_e32 v114, v8, v8
	v_fmac_f32_e32 v115, v10, v10
	v_add_f32_e32 v114, v114, v115
	v_add_f32_e32 v113, v114, v113
	v_mov_b32_e32 v114, v112
	v_mov_b32_e32 v115, v113
	s_nop 0
	v_permlane16_swap_b32_e32 v112, v114
	v_permlane16_swap_b32_e32 v113, v115
	v_add_f32_e32 v112, v112, v114
	v_add_f32_e32 v113, v113, v115
	v_mov_b32_e32 v114, v112
	v_mov_b32_e32 v115, v113
	s_nop 0
	v_permlane32_swap_b32_e32 v112, v114
	v_permlane32_swap_b32_e32 v113, v115
	s_and_saveexec_b64 s[60:61], s[8:9]
	v_pk_add_f32 v[112:113], v[112:113], v[114:115]
	ds_write_b64 v188, v[112:113] offset:5632
	s_or_b64 exec, exec, s[60:61]
	s_waitcnt lgkmcnt(0)
	s_barrier
	s_add_u32 s60, s22, 0x2ac00000
	v_add_u32_e32 v174, s82, v184
	s_addc_u32 s61, s23, 0
	v_ashrrev_i32_e32 v175, 31, v174
	s_and_saveexec_b64 vcc, s[10:11]
	s_cbranch_execz .LBB0_665
	ds_read_b128 v[112:115], v187
	ds_read_b128 v[120:123], v187 offset:16
	s_ashr_i32 s29, s28, 31
	s_waitcnt lgkmcnt(1)
	v_mov_b32_e32 v124, v112
	s_waitcnt lgkmcnt(0)
	v_mov_b32_e32 v125, v120
	v_mov_b32_e32 v126, v114
	v_mov_b32_e32 v127, v122
	v_pk_add_f32 v[124:125], v[124:125], v[126:127]
	v_mov_b32_e32 v120, v113
	v_mov_b32_e32 v122, v115
	v_add_f32_e32 v114, v124, v125
	v_pk_add_f32 v[112:113], v[120:121], v[122:123]
	s_nop 0
	v_add_f32_e32 v113, v112, v113
	v_mul_f32_e32 v112, 0x3b800000, v114
	v_fma_f32 v113, -v114, v112, v113
	v_lshlrev_b64 v[114:115], 6, v[174:175]
	v_lshl_add_u64 v[114:115], s[60:61], 0, v[114:115]
	v_max_f32_e32 v113, 0, v113
	v_lshl_add_u64 v[114:115], s[28:29], 3, v[114:115]
	global_store_dwordx2 v[114:115], v[112:113], off sc1

.LBB0_817:
	v_readlane_b32 s6, v254, 35
	s_waitcnt lgkmcnt(0)
	s_add_u32 s6, s26, s6
	s_addc_u32 s7, s27, 0
	s_add_u32 s45, s6, 0x100000
	s_addc_u32 s59, s7, 0
	s_lshr_b32 s6, s72, 14
	s_add_i32 s60, s6, 8
	s_ashr_i32 s61, s64, 4
	s_and_b64 s[6:7], s[18:19], exec
	s_cselect_b32 s6, s60, s61
	s_lshl_b32 s60, s82, 8
	s_mul_hi_i32 s7, s6, 0x4800
	s_mulk_i32 s6, 0x4800
	s_or_b32 s69, s60, s47
	s_lshl_b64 s[18:19], s[6:7], 2
	v_or_b32_e32 v132, s69, v181
	s_add_u32 s6, s45, s18
	s_addc_u32 s7, s59, s19
	v_ashrrev_i32_e32 v133, 31, v132
	v_lshl_add_u64 v[132:133], v[132:133], 2, s[6:7]
	s_mov_b32 s6, 0x10000
	v_add_co_u32_e32 v140, vcc, s6, v132
	v_lshl_add_u64 v[144:145], v[132:133], 0, s[76:77]
	s_nop 0
	v_addc_co_u32_e32 v141, vcc, 0, v133, vcc
	global_load_dwordx4 v[132:135], v[144:145], off offset:64
	global_load_dwordx4 v[136:139], v[144:145], off offset:512
	s_nop 0
	global_load_dwordx4 v[140:143], v[140:141], off
	s_nop 0
	global_load_dwordx4 v[152:155], v[144:145], off offset:576
	v_or3_b32 v144, v185, s47, v183
	v_add_u32_e32 v144, s60, v144
	v_ashrrev_i32_e32 v145, 31, v144
	v_readlane_b32 s6, v254, 46
	v_lshl_add_u64 v[178:179], v[144:145], 2, s[56:57]
	v_readlane_b32 s7, v254, 47
	v_lshl_add_u64 v[148:149], v[178:179], 0, s[36:37]
	global_load_dwordx4 v[144:147], v[148:149], off nt
	s_nop 0
	global_load_dwordx4 v[148:151], v[148:149], off offset:512 nt
	v_lshl_add_u64 v[166:167], v[178:179], 0, s[6:7]
	v_readlane_b32 s6, v254, 50
	global_load_dwordx4 v[156:159], v[166:167], off nt
	s_nop 0
	global_load_dwordx4 v[166:169], v[166:167], off offset:512 nt
	v_readlane_b32 s7, v254, 51
	v_lshl_add_u64 v[174:175], v[178:179], 0, s[42:43]
	global_load_dwordx4 v[170:173], v[174:175], off nt
	s_nop 0
	global_load_dwordx4 v[174:177], v[174:175], off offset:512 nt
	v_lshl_add_u64 v[196:197], v[178:179], 0, s[6:7]
	v_readlane_b32 s6, v254, 54
	v_readlane_b32 s7, v254, 55
	global_load_dwordx4 v[192:195], v[196:197], off nt
	s_nop 0
	global_load_dwordx4 v[196:199], v[196:197], off offset:512 nt
	v_lshl_add_u64 v[204:205], v[178:179], 0, s[48:49]
	v_lshl_add_u64 v[208:209], v[178:179], 0, s[6:7]
	v_readlane_b32 s6, v254, 58
	global_load_dwordx4 v[200:203], v[204:205], off nt
	s_nop 0
	global_load_dwordx4 v[204:207], v[204:205], off offset:512 nt
	s_nop 0
	global_load_dwordx4 v[214:217], v[208:209], off nt
	global_load_dwordx4 v[218:221], v[208:209], off offset:512 nt
	v_lshl_add_u64 v[208:209], v[178:179], 0, s[54:55]
	v_readlane_b32 s7, v254, 59
	global_load_dwordx4 v[222:225], v[208:209], off nt
	global_load_dwordx4 v[226:229], v[208:209], off offset:512 nt
	v_lshl_add_u64 v[208:209], v[178:179], 0, s[6:7]
	global_load_dwordx4 v[230:233], v[208:209], off nt
	global_load_dwordx4 v[234:237], v[208:209], off offset:512 nt
	s_waitcnt vmcnt(0)
	ds_write_b128 v184, v[144:147]
	ds_write_b128 v184, v[156:159] offset:1152
	ds_read_b128 v[144:147], v182
	ds_read_b128 v[238:241], v182 offset:64
	ds_write_b128 v184, v[148:151]
	ds_write_b128 v184, v[166:169] offset:1152
	ds_read_b128 v[148:151], v182
	ds_read_b128 v[250:253], v182 offset:64
	v_pk_add_f32 v[142:143], v[142:143], 1.0 op_sel_hi:[1,0]
	v_pk_add_f32 v[140:141], v[140:141], 1.0 op_sel_hi:[1,0]
	s_waitcnt lgkmcnt(5)
	v_pk_mul_f32 v[146:147], v[146:147], s[80:81] op_sel_hi:[1,0]
	v_pk_mul_f32 v[144:145], v[144:145], s[80:81] op_sel_hi:[1,0]
	v_pk_mul_f32 v[156:157], v[142:143], 0.5 op_sel_hi:[1,0]
	v_pk_mul_f32 v[158:159], v[140:141], 0.5 op_sel_hi:[1,0]
	ds_write_b128 v184, v[170:173]
	ds_write_b128 v184, v[192:195] offset:1152
	v_pk_fma_f32 v[142:143], v[130:131], v[156:157], v[146:147]
	v_pk_fma_f32 v[140:141], v[128:129], v[158:159], v[144:145]
	ds_read_b128 v[128:131], v182
	ds_read_b128 v[192:195], v182 offset:64
	v_pk_add_f32 v[134:135], v[134:135], 1.0 op_sel_hi:[1,0]
	v_pk_add_f32 v[132:133], v[132:133], 1.0 op_sel_hi:[1,0]
	s_waitcnt lgkmcnt(8)
	v_pk_mul_f32 v[144:145], v[240:241], s[80:81] op_sel_hi:[1,0]
	v_pk_mul_f32 v[208:209], v[238:239], s[80:81] op_sel_hi:[1,0]
	v_pk_mul_f32 v[166:167], v[134:135], 0.5 op_sel_hi:[1,0]
	v_pk_mul_f32 v[168:169], v[132:133], 0.5 op_sel_hi:[1,0]
	v_pk_fma_f32 v[146:147], v[126:127], v[166:167], v[144:145]
	v_pk_fma_f32 v[144:145], v[124:125], v[168:169], v[208:209]
	v_pk_add_f32 v[132:133], v[138:139], 1.0 op_sel_hi:[1,0]
	v_pk_add_f32 v[134:135], v[136:137], 1.0 op_sel_hi:[1,0]
	s_waitcnt lgkmcnt(5)
	v_pk_mul_f32 v[124:125], v[150:151], s[80:81] op_sel_hi:[1,0]
	v_pk_mul_f32 v[126:127], v[148:149], s[80:81] op_sel_hi:[1,0]
	v_pk_mul_f32 v[170:171], v[132:133], 0.5 op_sel_hi:[1,0]
	v_pk_mul_f32 v[172:173], v[134:135], 0.5 op_sel_hi:[1,0]
	ds_write_b128 v184, v[174:177]
	ds_write_b128 v184, v[196:199] offset:1152
	v_pk_fma_f32 v[150:151], v[122:123], v[170:171], v[124:125]
	v_pk_fma_f32 v[148:149], v[120:121], v[172:173], v[126:127]
	ds_read_b128 v[120:123], v182
	ds_read_b128 v[196:199], v182 offset:64
	v_pk_add_f32 v[132:133], v[154:155], 1.0 op_sel_hi:[1,0]
	v_pk_add_f32 v[134:135], v[152:153], 1.0 op_sel_hi:[1,0]
	s_waitcnt lgkmcnt(8)
	v_pk_mul_f32 v[124:125], v[252:253], s[80:81] op_sel_hi:[1,0]
	v_pk_mul_f32 v[126:127], v[250:251], s[80:81] op_sel_hi:[1,0]
	v_pk_mul_f32 v[174:175], v[132:133], 0.5 op_sel_hi:[1,0]
	v_pk_mul_f32 v[176:177], v[134:135], 0.5 op_sel_hi:[1,0]
	v_pk_fma_f32 v[154:155], v[110:111], v[174:175], v[124:125]
	v_pk_fma_f32 v[152:153], v[108:109], v[176:177], v[126:127]
	s_waitcnt lgkmcnt(5)
	v_pk_mul_f32 v[108:109], v[130:131], s[80:81] op_sel_hi:[1,0]
	v_pk_mul_f32 v[110:111], v[128:129], s[80:81] op_sel_hi:[1,0]
	v_pk_fma_f32 v[134:135], v[118:119], v[156:157], v[108:109]
	v_pk_fma_f32 v[132:133], v[116:117], v[158:159], v[110:111]
	s_waitcnt lgkmcnt(4)
	v_pk_mul_f32 v[108:109], v[194:195], s[80:81] op_sel_hi:[1,0]
	v_pk_mul_f32 v[110:111], v[192:193], s[80:81] op_sel_hi:[1,0]
	v_pk_fma_f32 v[138:139], v[114:115], v[166:167], v[108:109]
	v_pk_fma_f32 v[136:137], v[112:113], v[168:169], v[110:111]
	s_waitcnt lgkmcnt(1)
	v_pk_mul_f32 v[108:109], v[122:123], s[80:81] op_sel_hi:[1,0]
	v_pk_mul_f32 v[110:111], v[120:121], s[80:81] op_sel_hi:[1,0]
	v_pk_fma_f32 v[126:127], v[106:107], v[170:171], v[108:109]
	v_pk_fma_f32 v[124:125], v[104:105], v[172:173], v[110:111]
	s_waitcnt lgkmcnt(0)
	v_pk_mul_f32 v[104:105], v[198:199], s[80:81] op_sel_hi:[1,0]
	v_pk_mul_f32 v[106:107], v[196:197], s[80:81] op_sel_hi:[1,0]
	v_readlane_b32 s6, v254, 60
	v_pk_fma_f32 v[130:131], v[102:103], v[174:175], v[104:105]
	v_pk_fma_f32 v[128:129], v[100:101], v[176:177], v[106:107]
	v_readlane_b32 s7, v254, 61
	v_lshl_add_u64 v[104:105], v[178:179], 0, s[62:63]
	global_load_dwordx4 v[100:103], v[104:105], off nt
	s_nop 0
	global_load_dwordx4 v[104:107], v[104:105], off offset:512 nt
	v_lshl_add_u64 v[108:109], v[178:179], 0, s[6:7]
	v_readlane_b32 s6, v254, 62
	global_load_dwordx4 v[112:115], v[108:109], off nt
	global_load_dwordx4 v[192:195], v[108:109], off offset:512 nt
	v_lshl_add_u64 v[108:109], v[178:179], 0, s[96:97]
	v_readlane_b32 s7, v254, 63
	global_load_dwordx4 v[196:199], v[108:109], off nt
	global_load_dwordx4 v[238:241], v[108:109], off offset:512 nt
	v_lshl_add_u64 v[108:109], v[178:179], 0, s[6:7]
	global_load_dwordx4 v[250:253], v[108:109], off nt
	global_load_dwordx4 v[208:211], v[108:109], off offset:512 nt
	ds_write_b128 v184, v[200:203]
	ds_write_b128 v184, v[214:217] offset:1152
	ds_read_b128 v[108:111], v182
	ds_read_b128 v[120:123], v182 offset:64
	ds_write_b128 v184, v[204:207]
	ds_write_b128 v184, v[218:221] offset:1152
	ds_read_b128 v[200:203], v182
	ds_read_b128 v[204:207], v182 offset:64
	ds_write_b128 v184, v[222:225]
	ds_write_b128 v184, v[230:233] offset:1152
	ds_read_b128 v[214:217], v182
	ds_read_b128 v[218:221], v182 offset:64
	s_waitcnt lgkmcnt(9)
	v_pk_mul_f32 v[110:111], v[110:111], s[80:81] op_sel_hi:[1,0]
	v_pk_mul_f32 v[108:109], v[108:109], s[80:81] op_sel_hi:[1,0]
	v_pk_fma_f32 v[118:119], v[98:99], v[156:157], v[110:111]
	v_pk_fma_f32 v[116:117], v[96:97], v[158:159], v[108:109]
	s_waitcnt lgkmcnt(8)
	v_pk_mul_f32 v[96:97], v[122:123], s[80:81] op_sel_hi:[1,0]
	v_pk_mul_f32 v[98:99], v[120:121], s[80:81] op_sel_hi:[1,0]
	v_pk_fma_f32 v[122:123], v[94:95], v[166:167], v[96:97]
	v_pk_fma_f32 v[120:121], v[92:93], v[168:169], v[98:99]
	s_waitcnt lgkmcnt(5)
	v_pk_mul_f32 v[92:93], v[202:203], s[80:81] op_sel_hi:[1,0]
	v_pk_mul_f32 v[94:95], v[200:201], s[80:81] op_sel_hi:[1,0]
	ds_write_b128 v184, v[226:229]
	ds_write_b128 v184, v[234:237] offset:1152
	v_pk_fma_f32 v[98:99], v[90:91], v[170:171], v[92:93]
	v_pk_fma_f32 v[96:97], v[88:89], v[172:173], v[94:95]
	ds_read_b128 v[88:91], v182
	ds_read_b128 v[92:95], v182 offset:64
	s_waitcnt lgkmcnt(8)
	v_pk_mul_f32 v[108:109], v[206:207], s[80:81] op_sel_hi:[1,0]
	v_pk_mul_f32 v[200:201], v[204:205], s[80:81] op_sel_hi:[1,0]
	v_pk_fma_f32 v[110:111], v[74:75], v[174:175], v[108:109]
	v_pk_fma_f32 v[108:109], v[72:73], v[176:177], v[200:201]
	s_waitcnt lgkmcnt(5)
	v_pk_mul_f32 v[72:73], v[216:217], s[80:81] op_sel_hi:[1,0]
	v_pk_mul_f32 v[74:75], v[214:215], s[80:81] op_sel_hi:[1,0]
	v_pk_fma_f32 v[82:83], v[82:83], v[156:157], v[72:73]
	v_pk_fma_f32 v[80:81], v[80:81], v[158:159], v[74:75]
	s_waitcnt lgkmcnt(4)
	v_pk_mul_f32 v[72:73], v[220:221], s[80:81] op_sel_hi:[1,0]
	v_pk_mul_f32 v[74:75], v[218:219], s[80:81] op_sel_hi:[1,0]
	v_pk_fma_f32 v[86:87], v[86:87], v[166:167], v[72:73]
	v_pk_fma_f32 v[84:85], v[84:85], v[168:169], v[74:75]
	s_waitcnt lgkmcnt(1)
	v_pk_mul_f32 v[72:73], v[90:91], s[80:81] op_sel_hi:[1,0]
	v_pk_mul_f32 v[74:75], v[88:89], s[80:81] op_sel_hi:[1,0]
	v_pk_fma_f32 v[70:71], v[70:71], v[170:171], v[72:73]
	s_waitcnt lgkmcnt(0)
	v_pk_mul_f32 v[72:73], v[94:95], s[80:81] op_sel_hi:[1,0]
	v_pk_mul_f32 v[88:89], v[92:93], s[80:81] op_sel_hi:[1,0]
	v_pk_fma_f32 v[68:69], v[68:69], v[172:173], v[74:75]
	v_pk_fma_f32 v[74:75], v[66:67], v[174:175], v[72:73]
	v_pk_fma_f32 v[72:73], v[64:65], v[176:177], v[88:89]
	v_readlane_b32 s6, v255, 0
	v_lshl_add_u64 v[64:65], v[178:179], 0, s[70:71]
	v_readlane_b32 s7, v255, 1
	global_load_dwordx4 v[88:91], v[64:65], off nt
	global_load_dwordx4 v[92:95], v[64:65], off offset:512 nt
	v_lshl_add_u64 v[64:65], v[178:179], 0, s[6:7]
	v_readlane_b32 s6, v255, 2
	global_load_dwordx4 v[200:203], v[64:65], off nt
	global_load_dwordx4 v[204:207], v[64:65], off offset:512 nt
	v_lshl_add_u64 v[64:65], v[178:179], 0, s[14:15]
	v_readlane_b32 s7, v255, 3
	global_load_dwordx4 v[214:217], v[64:65], off nt
	global_load_dwordx4 v[218:221], v[64:65], off offset:512 nt
	v_lshl_add_u64 v[64:65], v[178:179], 0, s[6:7]
	global_load_dwordx4 v[222:225], v[64:65], off nt
	global_load_dwordx4 v[226:229], v[64:65], off offset:512 nt
	s_waitcnt vmcnt(15)
	ds_write_b128 v184, v[100:103]
	s_waitcnt vmcnt(13)
	ds_write_b128 v184, v[112:115] offset:1152
	ds_read_b128 v[64:67], v182
	ds_read_b128 v[100:103], v182 offset:64
	ds_write_b128 v184, v[104:107]
	s_waitcnt vmcnt(12)
	ds_write_b128 v184, v[192:195] offset:1152
	ds_read_b128 v[104:107], v182
	ds_read_b128 v[112:115], v182 offset:64
	s_waitcnt vmcnt(11)
	ds_write_b128 v184, v[196:199]
	s_waitcnt vmcnt(9)
	ds_write_b128 v184, v[250:253] offset:1152
	ds_read_b128 v[192:195], v182
	ds_read_b128 v[196:199], v182 offset:64
	s_waitcnt lgkmcnt(9)
	v_pk_mul_f32 v[64:65], v[64:65], s[80:81] op_sel_hi:[1,0]
	v_pk_mul_f32 v[66:67], v[66:67], s[80:81] op_sel_hi:[1,0]
	v_pk_fma_f32 v[60:61], v[60:61], v[158:159], v[64:65]
	s_waitcnt lgkmcnt(8)
	v_pk_mul_f32 v[64:65], v[102:103], s[80:81] op_sel_hi:[1,0]
	v_pk_mul_f32 v[100:101], v[100:101], s[80:81] op_sel_hi:[1,0]
	v_pk_fma_f32 v[62:63], v[62:63], v[156:157], v[66:67]
	v_pk_fma_f32 v[66:67], v[58:59], v[166:167], v[64:65]
	v_pk_fma_f32 v[64:65], v[56:57], v[168:169], v[100:101]
	ds_write_b128 v184, v[238:241]
	s_waitcnt vmcnt(8)
	ds_write_b128 v184, v[208:211] offset:1152
	s_waitcnt lgkmcnt(7)
	v_pk_mul_f32 v[56:57], v[106:107], s[80:81] op_sel_hi:[1,0]
	v_pk_mul_f32 v[58:59], v[104:105], s[80:81] op_sel_hi:[1,0]
	ds_read_b128 v[100:103], v182
	ds_read_b128 v[104:107], v182 offset:64
	v_pk_fma_f32 v[54:55], v[54:55], v[170:171], v[56:57]
	s_waitcnt lgkmcnt(8)
	v_pk_mul_f32 v[56:57], v[114:115], s[80:81] op_sel_hi:[1,0]
	v_pk_mul_f32 v[112:113], v[112:113], s[80:81] op_sel_hi:[1,0]
	v_pk_fma_f32 v[52:53], v[52:53], v[172:173], v[58:59]
	v_pk_fma_f32 v[58:59], v[42:43], v[174:175], v[56:57]
	v_pk_fma_f32 v[56:57], v[40:41], v[176:177], v[112:113]
	s_waitcnt lgkmcnt(5)
	v_pk_mul_f32 v[40:41], v[194:195], s[80:81] op_sel_hi:[1,0]
	v_pk_mul_f32 v[42:43], v[192:193], s[80:81] op_sel_hi:[1,0]
	v_pk_fma_f32 v[46:47], v[46:47], v[156:157], v[40:41]
	v_pk_fma_f32 v[44:45], v[44:45], v[158:159], v[42:43]
	s_waitcnt lgkmcnt(4)
	v_pk_mul_f32 v[40:41], v[198:199], s[80:81] op_sel_hi:[1,0]
	v_pk_mul_f32 v[42:43], v[196:197], s[80:81] op_sel_hi:[1,0]
	v_pk_fma_f32 v[50:51], v[50:51], v[166:167], v[40:41]
	v_pk_fma_f32 v[48:49], v[48:49], v[168:169], v[42:43]
	s_waitcnt lgkmcnt(1)
	v_pk_mul_f32 v[40:41], v[102:103], s[80:81] op_sel_hi:[1,0]
	v_pk_mul_f32 v[42:43], v[100:101], s[80:81] op_sel_hi:[1,0]
	v_pk_fma_f32 v[38:39], v[38:39], v[170:171], v[40:41]
	s_waitcnt lgkmcnt(0)
	v_pk_mul_f32 v[40:41], v[106:107], s[80:81] op_sel_hi:[1,0]
	v_pk_mul_f32 v[100:101], v[104:105], s[80:81] op_sel_hi:[1,0]
	v_pk_fma_f32 v[36:37], v[36:37], v[172:173], v[42:43]
	v_pk_fma_f32 v[42:43], v[34:35], v[174:175], v[40:41]
	v_pk_fma_f32 v[40:41], v[32:33], v[176:177], v[100:101]
	s_nop 0
	s_waitcnt vmcnt(7)
	ds_write_b128 v184, v[88:91]
	s_waitcnt vmcnt(5)
	ds_write_b128 v184, v[200:203] offset:1152
	ds_read_b128 v[32:35], v182
	ds_read_b128 v[88:91], v182 offset:64
	ds_write_b128 v184, v[92:95]
	s_waitcnt vmcnt(4)
	ds_write_b128 v184, v[204:207] offset:1152
	ds_read_b128 v[92:95], v182
	ds_read_b128 v[100:103], v182 offset:64
	s_waitcnt vmcnt(3)
	ds_write_b128 v184, v[214:217]
	s_waitcnt vmcnt(1)
	ds_write_b128 v184, v[222:225] offset:1152
	ds_read_b128 v[104:107], v182
	ds_read_b128 v[112:115], v182 offset:64
	s_waitcnt lgkmcnt(9)
	v_pk_mul_f32 v[32:33], v[32:33], s[80:81] op_sel_hi:[1,0]
	v_pk_mul_f32 v[34:35], v[34:35], s[80:81] op_sel_hi:[1,0]
	v_pk_fma_f32 v[28:29], v[28:29], v[158:159], v[32:33]
	s_waitcnt lgkmcnt(8)
	v_pk_mul_f32 v[32:33], v[90:91], s[80:81] op_sel_hi:[1,0]
	v_pk_mul_f32 v[88:89], v[88:89], s[80:81] op_sel_hi:[1,0]
	v_pk_fma_f32 v[30:31], v[30:31], v[156:157], v[34:35]
	v_pk_fma_f32 v[34:35], v[26:27], v[166:167], v[32:33]
	v_pk_fma_f32 v[32:33], v[24:25], v[168:169], v[88:89]
	ds_write_b128 v184, v[218:221]
	s_waitcnt vmcnt(0)
	ds_write_b128 v184, v[226:229] offset:1152
	s_waitcnt lgkmcnt(7)
	v_pk_mul_f32 v[24:25], v[94:95], s[80:81] op_sel_hi:[1,0]
	v_pk_mul_f32 v[26:27], v[92:93], s[80:81] op_sel_hi:[1,0]
	ds_read_b128 v[88:91], v182
	ds_read_b128 v[92:95], v182 offset:64
	v_pk_fma_f32 v[22:23], v[22:23], v[170:171], v[24:25]
	s_waitcnt lgkmcnt(8)
	v_pk_mul_f32 v[24:25], v[102:103], s[80:81] op_sel_hi:[1,0]
	v_pk_mul_f32 v[100:101], v[100:101], s[80:81] op_sel_hi:[1,0]
	v_pk_fma_f32 v[20:21], v[20:21], v[172:173], v[26:27]
	v_pk_fma_f32 v[26:27], v[14:15], v[174:175], v[24:25]
	v_pk_fma_f32 v[24:25], v[12:13], v[176:177], v[100:101]
	s_waitcnt lgkmcnt(5)
	v_pk_mul_f32 v[12:13], v[106:107], s[80:81] op_sel_hi:[1,0]
	v_pk_mul_f32 v[100:101], v[104:105], s[80:81] op_sel_hi:[1,0]
	v_pk_fma_f32 v[14:15], v[78:79], v[156:157], v[12:13]
	v_pk_fma_f32 v[12:13], v[76:77], v[158:159], v[100:101]
	s_waitcnt lgkmcnt(4)
	v_pk_mul_f32 v[76:77], v[114:115], s[80:81] op_sel_hi:[1,0]
	v_pk_mul_f32 v[78:79], v[112:113], s[80:81] op_sel_hi:[1,0]
	v_pk_fma_f32 v[18:19], v[18:19], v[166:167], v[76:77]
	v_pk_fma_f32 v[16:17], v[16:17], v[168:169], v[78:79]
	s_waitcnt lgkmcnt(1)
	v_pk_mul_f32 v[76:77], v[90:91], s[80:81] op_sel_hi:[1,0]
	v_pk_mul_f32 v[78:79], v[88:89], s[80:81] op_sel_hi:[1,0]
	v_pk_fma_f32 v[6:7], v[6:7], v[170:171], v[76:77]
	s_waitcnt lgkmcnt(0)
	v_pk_mul_f32 v[76:77], v[94:95], s[80:81] op_sel_hi:[1,0]
	v_pk_fma_f32 v[4:5], v[4:5], v[172:173], v[78:79]
	v_pk_mul_f32 v[78:79], v[92:93], s[80:81] op_sel_hi:[1,0]
	v_pk_fma_f32 v[10:11], v[10:11], v[174:175], v[76:77]
	v_add_f32_e32 v76, v140, v141
	v_add_f32_e32 v77, v142, v143
	v_pk_fma_f32 v[8:9], v[8:9], v[176:177], v[78:79]
	v_add_f32_e32 v76, v76, v77
	v_mul_f32_e32 v77, v141, v141
	v_mul_f32_e32 v78, v143, v143
	v_fmac_f32_e32 v77, v140, v140
	v_fmac_f32_e32 v78, v142, v142
	v_add_f32_e32 v77, v77, v78
	v_add_f32_e32 v78, v144, v145
	v_add_f32_e32 v79, v146, v147
	v_add_f32_e32 v76, 0, v76
	v_add_f32_e32 v78, v78, v79
	v_add_f32_e32 v76, v78, v76
	v_mul_f32_e32 v78, v145, v145
	v_mul_f32_e32 v79, v147, v147
	v_fmac_f32_e32 v78, v144, v144
	v_fmac_f32_e32 v79, v146, v146
	v_add_f32_e32 v78, v78, v79
	v_add_f32_e32 v77, v77, v78
	v_add_f32_e32 v78, v148, v149
	v_add_f32_e32 v79, v150, v151
	v_add_f32_e32 v78, v78, v79
	v_add_f32_e32 v76, v78, v76
	v_mul_f32_e32 v78, v149, v149
	v_mul_f32_e32 v79, v151, v151
	v_fmac_f32_e32 v78, v148, v148
	v_fmac_f32_e32 v79, v150, v150
	v_add_f32_e32 v78, v78, v79
	v_add_f32_e32 v77, v78, v77
	v_add_f32_e32 v78, v152, v153
	v_add_f32_e32 v79, v154, v155
	v_add_f32_e32 v78, v78, v79
	v_add_f32_e32 v76, v78, v76
	v_mul_f32_e32 v78, v153, v153
	v_mul_f32_e32 v79, v155, v155
	v_fmac_f32_e32 v78, v152, v152
	v_fmac_f32_e32 v79, v154, v154
	v_add_f32_e32 v78, v78, v79
	v_add_f32_e32 v77, v78, v77
	v_mov_b32_e32 v78, v76
	v_mov_b32_e32 v79, v77
	s_nop 0
	v_permlane16_swap_b32_e32 v76, v78
	v_permlane16_swap_b32_e32 v77, v79
	v_add_f32_e32 v76, v76, v78
	v_add_f32_e32 v77, v77, v79
	v_mov_b32_e32 v78, v76
	v_mov_b32_e32 v79, v77
	s_nop 0
	v_permlane32_swap_b32_e32 v76, v78
	v_permlane32_swap_b32_e32 v77, v79
	s_and_saveexec_b64 s[6:7], s[8:9]
	v_pk_add_f32 v[76:77], v[76:77], v[78:79]
	ds_write_b64 v190, v[76:77]
	s_or_b64 exec, exec, s[6:7]
	v_add_f32_e32 v76, v132, v133
	v_add_f32_e32 v77, v134, v135
	v_add_f32_e32 v76, v76, v77
	v_mul_f32_e32 v77, v133, v133
	v_mul_f32_e32 v78, v135, v135
	v_fmac_f32_e32 v77, v132, v132
	v_fmac_f32_e32 v78, v134, v134
	v_add_f32_e32 v77, v77, v78
	v_add_f32_e32 v78, v136, v137
	v_add_f32_e32 v79, v138, v139
	v_add_f32_e32 v76, 0, v76
	v_add_f32_e32 v78, v78, v79
	v_add_f32_e32 v76, v78, v76
	v_mul_f32_e32 v78, v137, v137
	v_mul_f32_e32 v79, v139, v139
	v_fmac_f32_e32 v78, v136, v136
	v_fmac_f32_e32 v79, v138, v138
	v_add_f32_e32 v78, v78, v79
	v_add_f32_e32 v77, v77, v78
	v_add_f32_e32 v78, v124, v125
	v_add_f32_e32 v79, v126, v127
	v_add_f32_e32 v78, v78, v79
	v_add_f32_e32 v76, v78, v76
	v_mul_f32_e32 v78, v125, v125
	v_mul_f32_e32 v79, v127, v127
	v_fmac_f32_e32 v78, v124, v124
	v_fmac_f32_e32 v79, v126, v126
	v_add_f32_e32 v78, v78, v79
	v_add_f32_e32 v77, v78, v77
	v_add_f32_e32 v78, v128, v129
	v_add_f32_e32 v79, v130, v131
	v_add_f32_e32 v78, v78, v79
	v_add_f32_e32 v76, v78, v76
	v_mul_f32_e32 v78, v129, v129
	v_mul_f32_e32 v79, v131, v131
	v_fmac_f32_e32 v78, v128, v128
	v_fmac_f32_e32 v79, v130, v130
	v_add_f32_e32 v78, v78, v79
	v_add_f32_e32 v77, v78, v77
	v_mov_b32_e32 v78, v76
	v_mov_b32_e32 v79, v77
	s_nop 0
	v_permlane16_swap_b32_e32 v76, v78
	v_permlane16_swap_b32_e32 v77, v79
	v_add_f32_e32 v76, v76, v78
	v_add_f32_e32 v77, v77, v79
	v_mov_b32_e32 v78, v76
	v_mov_b32_e32 v79, v77
	s_nop 0
	v_permlane32_swap_b32_e32 v76, v78
	v_permlane32_swap_b32_e32 v77, v79
	s_and_saveexec_b64 s[6:7], s[8:9]
	v_pk_add_f32 v[76:77], v[76:77], v[78:79]
	ds_write_b64 v190, v[76:77] offset:512
	s_or_b64 exec, exec, s[6:7]
	v_add_f32_e32 v76, v116, v117
	v_add_f32_e32 v77, v118, v119
	v_add_f32_e32 v76, v76, v77
	v_mul_f32_e32 v77, v117, v117
	v_mul_f32_e32 v78, v119, v119
	v_fmac_f32_e32 v77, v116, v116
	v_fmac_f32_e32 v78, v118, v118
	v_add_f32_e32 v77, v77, v78
	v_add_f32_e32 v78, v120, v121
	v_add_f32_e32 v79, v122, v123
	v_add_f32_e32 v76, 0, v76
	v_add_f32_e32 v78, v78, v79
	v_add_f32_e32 v76, v78, v76
	v_mul_f32_e32 v78, v121, v121
	v_mul_f32_e32 v79, v123, v123
	v_fmac_f32_e32 v78, v120, v120
	v_fmac_f32_e32 v79, v122, v122
	v_add_f32_e32 v78, v78, v79
	v_add_f32_e32 v77, v77, v78
	v_add_f32_e32 v78, v96, v97
	v_add_f32_e32 v79, v98, v99
	v_add_f32_e32 v78, v78, v79
	v_add_f32_e32 v76, v78, v76
	v_mul_f32_e32 v78, v97, v97
	v_mul_f32_e32 v79, v99, v99
	v_fmac_f32_e32 v78, v96, v96
	v_fmac_f32_e32 v79, v98, v98
	v_add_f32_e32 v78, v78, v79
	v_add_f32_e32 v77, v78, v77
	v_add_f32_e32 v78, v108, v109
	v_add_f32_e32 v79, v110, v111
	v_add_f32_e32 v78, v78, v79
	v_add_f32_e32 v76, v78, v76
	v_mul_f32_e32 v78, v109, v109
	v_mul_f32_e32 v79, v111, v111
	v_fmac_f32_e32 v78, v108, v108
	v_fmac_f32_e32 v79, v110, v110
	v_add_f32_e32 v78, v78, v79
	v_add_f32_e32 v77, v78, v77
	v_mov_b32_e32 v78, v76
	v_mov_b32_e32 v79, v77
	s_nop 0
	v_permlane16_swap_b32_e32 v76, v78
	v_permlane16_swap_b32_e32 v77, v79
	v_add_f32_e32 v76, v76, v78
	v_add_f32_e32 v77, v77, v79
	v_mov_b32_e32 v78, v76
	v_mov_b32_e32 v79, v77
	s_nop 0
	v_permlane32_swap_b32_e32 v76, v78
	v_permlane32_swap_b32_e32 v77, v79
	s_and_saveexec_b64 s[6:7], s[8:9]
	v_pk_add_f32 v[76:77], v[76:77], v[78:79]
	ds_write_b64 v190, v[76:77] offset:1024
	s_or_b64 exec, exec, s[6:7]
	v_add_f32_e32 v76, v80, v81
	v_add_f32_e32 v77, v82, v83
	v_add_f32_e32 v76, v76, v77
	v_mul_f32_e32 v77, v81, v81
	v_mul_f32_e32 v78, v83, v83
	v_fmac_f32_e32 v77, v80, v80
	v_fmac_f32_e32 v78, v82, v82
	v_add_f32_e32 v77, v77, v78
	v_add_f32_e32 v78, v84, v85
	v_add_f32_e32 v79, v86, v87
	v_add_f32_e32 v76, 0, v76
	v_add_f32_e32 v78, v78, v79
	v_add_f32_e32 v76, v78, v76
	v_mul_f32_e32 v78, v85, v85
	v_mul_f32_e32 v79, v87, v87
	v_fmac_f32_e32 v78, v84, v84
	v_fmac_f32_e32 v79, v86, v86
	v_add_f32_e32 v78, v78, v79
	v_add_f32_e32 v77, v77, v78
	v_add_f32_e32 v78, v68, v69
	v_add_f32_e32 v79, v70, v71
	v_add_f32_e32 v78, v78, v79
	v_add_f32_e32 v76, v78, v76
	v_mul_f32_e32 v78, v69, v69
	v_mul_f32_e32 v79, v71, v71
	v_fmac_f32_e32 v78, v68, v68
	v_fmac_f32_e32 v79, v70, v70
	v_add_f32_e32 v78, v78, v79
	v_add_f32_e32 v77, v78, v77
	v_add_f32_e32 v78, v72, v73
	v_add_f32_e32 v79, v74, v75
	v_add_f32_e32 v78, v78, v79
	v_add_f32_e32 v76, v78, v76
	v_mul_f32_e32 v78, v73, v73
	v_mul_f32_e32 v79, v75, v75
	v_fmac_f32_e32 v78, v72, v72
	v_fmac_f32_e32 v79, v74, v74
	v_add_f32_e32 v78, v78, v79
	v_add_f32_e32 v77, v78, v77
	v_mov_b32_e32 v78, v76
	v_mov_b32_e32 v79, v77
	s_nop 0
	v_permlane16_swap_b32_e32 v76, v78
	v_permlane16_swap_b32_e32 v77, v79
	v_add_f32_e32 v76, v76, v78
	v_add_f32_e32 v77, v77, v79
	v_mov_b32_e32 v78, v76
	v_mov_b32_e32 v79, v77
	s_nop 0
	v_permlane32_swap_b32_e32 v76, v78
	v_permlane32_swap_b32_e32 v77, v79
	s_and_saveexec_b64 s[6:7], s[8:9]
	v_pk_add_f32 v[76:77], v[76:77], v[78:79]
	ds_write_b64 v190, v[76:77] offset:1536
	s_or_b64 exec, exec, s[6:7]
	v_add_f32_e32 v76, v60, v61
	v_add_f32_e32 v77, v62, v63
	v_add_f32_e32 v76, v76, v77
	v_mul_f32_e32 v77, v61, v61
	v_mul_f32_e32 v78, v63, v63
	v_fmac_f32_e32 v77, v60, v60
	v_fmac_f32_e32 v78, v62, v62
	v_add_f32_e32 v77, v77, v78
	v_add_f32_e32 v78, v64, v65
	v_add_f32_e32 v79, v66, v67
	v_add_f32_e32 v76, 0, v76
	v_add_f32_e32 v78, v78, v79
	v_add_f32_e32 v76, v78, v76
	v_mul_f32_e32 v78, v65, v65
	v_mul_f32_e32 v79, v67, v67
	v_fmac_f32_e32 v78, v64, v64
	v_fmac_f32_e32 v79, v66, v66
	v_add_f32_e32 v78, v78, v79
	v_add_f32_e32 v77, v77, v78
	v_add_f32_e32 v78, v52, v53
	v_add_f32_e32 v79, v54, v55
	v_add_f32_e32 v78, v78, v79
	v_add_f32_e32 v76, v78, v76
	v_mul_f32_e32 v78, v53, v53
	v_mul_f32_e32 v79, v55, v55
	v_fmac_f32_e32 v78, v52, v52
	v_fmac_f32_e32 v79, v54, v54
	v_add_f32_e32 v78, v78, v79
	v_add_f32_e32 v77, v78, v77
	v_add_f32_e32 v78, v56, v57
	v_add_f32_e32 v79, v58, v59
	v_add_f32_e32 v78, v78, v79
	v_add_f32_e32 v76, v78, v76
	v_mul_f32_e32 v78, v57, v57
	v_mul_f32_e32 v79, v59, v59
	v_fmac_f32_e32 v78, v56, v56
	v_fmac_f32_e32 v79, v58, v58
	v_add_f32_e32 v78, v78, v79
	v_add_f32_e32 v77, v78, v77
	v_mov_b32_e32 v78, v76
	v_mov_b32_e32 v79, v77
	s_nop 0
	v_permlane16_swap_b32_e32 v76, v78
	v_permlane16_swap_b32_e32 v77, v79
	v_add_f32_e32 v76, v76, v78
	v_add_f32_e32 v77, v77, v79
	v_mov_b32_e32 v78, v76
	v_mov_b32_e32 v79, v77
	s_nop 0
	v_permlane32_swap_b32_e32 v76, v78
	v_permlane32_swap_b32_e32 v77, v79
	s_and_saveexec_b64 s[6:7], s[8:9]
	v_pk_add_f32 v[76:77], v[76:77], v[78:79]
	ds_write_b64 v190, v[76:77] offset:4096
	s_or_b64 exec, exec, s[6:7]
	v_add_f32_e32 v76, v44, v45
	v_add_f32_e32 v77, v46, v47
	v_add_f32_e32 v76, v76, v77
	v_mul_f32_e32 v77, v45, v45
	v_mul_f32_e32 v78, v47, v47
	v_fmac_f32_e32 v77, v44, v44
	v_fmac_f32_e32 v78, v46, v46
	v_add_f32_e32 v77, v77, v78
	v_add_f32_e32 v78, v48, v49
	v_add_f32_e32 v79, v50, v51
	v_add_f32_e32 v76, 0, v76
	v_add_f32_e32 v78, v78, v79
	v_add_f32_e32 v76, v78, v76
	v_mul_f32_e32 v78, v49, v49
	v_mul_f32_e32 v79, v51, v51
	v_fmac_f32_e32 v78, v48, v48
	v_fmac_f32_e32 v79, v50, v50
	v_add_f32_e32 v78, v78, v79
	v_add_f32_e32 v77, v77, v78
	v_add_f32_e32 v78, v36, v37
	v_add_f32_e32 v79, v38, v39
	v_add_f32_e32 v78, v78, v79
	v_add_f32_e32 v76, v78, v76
	v_mul_f32_e32 v78, v37, v37
	v_mul_f32_e32 v79, v39, v39
	v_fmac_f32_e32 v78, v36, v36
	v_fmac_f32_e32 v79, v38, v38
	v_add_f32_e32 v78, v78, v79
	v_add_f32_e32 v77, v78, v77
	v_add_f32_e32 v78, v40, v41
	v_add_f32_e32 v79, v42, v43
	v_add_f32_e32 v78, v78, v79
	v_add_f32_e32 v76, v78, v76
	v_mul_f32_e32 v78, v41, v41
	v_mul_f32_e32 v79, v43, v43
	v_fmac_f32_e32 v78, v40, v40
	v_fmac_f32_e32 v79, v42, v42
	v_add_f32_e32 v78, v78, v79
	v_add_f32_e32 v77, v78, v77
	v_mov_b32_e32 v78, v76
	v_mov_b32_e32 v79, v77
	s_nop 0
	v_permlane16_swap_b32_e32 v76, v78
	v_permlane16_swap_b32_e32 v77, v79
	v_add_f32_e32 v76, v76, v78
	v_add_f32_e32 v77, v77, v79
	v_mov_b32_e32 v78, v76
	v_mov_b32_e32 v79, v77
	s_nop 0
	v_permlane32_swap_b32_e32 v76, v78
	v_permlane32_swap_b32_e32 v77, v79
	s_and_saveexec_b64 s[6:7], s[8:9]
	v_pk_add_f32 v[76:77], v[76:77], v[78:79]
	ds_write_b64 v190, v[76:77] offset:4608
	s_or_b64 exec, exec, s[6:7]
	v_add_f32_e32 v76, v28, v29
	v_add_f32_e32 v77, v30, v31
	v_add_f32_e32 v76, v76, v77
	v_mul_f32_e32 v77, v29, v29
	v_mul_f32_e32 v78, v31, v31
	v_fmac_f32_e32 v77, v28, v28
	v_fmac_f32_e32 v78, v30, v30
	v_add_f32_e32 v77, v77, v78
	v_add_f32_e32 v78, v32, v33
	v_add_f32_e32 v79, v34, v35
	v_add_f32_e32 v76, 0, v76
	v_add_f32_e32 v78, v78, v79
	v_add_f32_e32 v76, v78, v76
	v_mul_f32_e32 v78, v33, v33
	v_mul_f32_e32 v79, v35, v35
	v_fmac_f32_e32 v78, v32, v32
	v_fmac_f32_e32 v79, v34, v34
	v_add_f32_e32 v78, v78, v79
	v_add_f32_e32 v77, v77, v78
	v_add_f32_e32 v78, v20, v21
	v_add_f32_e32 v79, v22, v23
	v_add_f32_e32 v78, v78, v79
	v_add_f32_e32 v76, v78, v76
	v_mul_f32_e32 v78, v21, v21
	v_mul_f32_e32 v79, v23, v23
	v_fmac_f32_e32 v78, v20, v20
	v_fmac_f32_e32 v79, v22, v22
	v_add_f32_e32 v78, v78, v79
	v_add_f32_e32 v77, v78, v77
	v_add_f32_e32 v78, v24, v25
	v_add_f32_e32 v79, v26, v27
	v_add_f32_e32 v78, v78, v79
	v_add_f32_e32 v76, v78, v76
	v_mul_f32_e32 v78, v25, v25
	v_mul_f32_e32 v79, v27, v27
	v_fmac_f32_e32 v78, v24, v24
	v_fmac_f32_e32 v79, v26, v26
	v_add_f32_e32 v78, v78, v79
	v_add_f32_e32 v77, v78, v77
	v_mov_b32_e32 v78, v76
	v_mov_b32_e32 v79, v77
	s_nop 0
	v_permlane16_swap_b32_e32 v76, v78
	v_permlane16_swap_b32_e32 v77, v79
	v_add_f32_e32 v76, v76, v78
	v_add_f32_e32 v77, v77, v79
	v_mov_b32_e32 v78, v76
	v_mov_b32_e32 v79, v77
	s_nop 0
	v_permlane32_swap_b32_e32 v76, v78
	v_permlane32_swap_b32_e32 v77, v79
	s_and_saveexec_b64 s[6:7], s[8:9]
	v_pk_add_f32 v[76:77], v[76:77], v[78:79]
	ds_write_b64 v190, v[76:77] offset:5120
	s_or_b64 exec, exec, s[6:7]
	v_add_f32_e32 v76, v12, v13
	v_add_f32_e32 v77, v14, v15
	v_add_f32_e32 v76, v76, v77
	v_mul_f32_e32 v77, v13, v13
	v_mul_f32_e32 v78, v15, v15
	v_fmac_f32_e32 v77, v12, v12
	v_fmac_f32_e32 v78, v14, v14
	v_add_f32_e32 v77, v77, v78
	v_add_f32_e32 v78, v16, v17
	v_add_f32_e32 v79, v18, v19
	v_add_f32_e32 v76, 0, v76
	v_add_f32_e32 v78, v78, v79
	v_add_f32_e32 v76, v78, v76
	v_mul_f32_e32 v78, v17, v17
	v_mul_f32_e32 v79, v19, v19
	v_fmac_f32_e32 v78, v16, v16
	v_fmac_f32_e32 v79, v18, v18
	v_add_f32_e32 v78, v78, v79
	v_add_f32_e32 v77, v77, v78
	v_add_f32_e32 v78, v4, v5
	v_add_f32_e32 v79, v6, v7
	v_add_f32_e32 v78, v78, v79
	v_add_f32_e32 v76, v78, v76
	v_mul_f32_e32 v78, v5, v5
	v_mul_f32_e32 v79, v7, v7
	v_fmac_f32_e32 v78, v4, v4
	v_fmac_f32_e32 v79, v6, v6
	v_add_f32_e32 v78, v78, v79
	v_add_f32_e32 v77, v78, v77
	v_add_f32_e32 v78, v8, v9
	v_add_f32_e32 v79, v10, v11
	v_add_f32_e32 v78, v78, v79
	v_add_f32_e32 v76, v78, v76
	v_mul_f32_e32 v78, v9, v9
	v_mul_f32_e32 v79, v11, v11
	v_fmac_f32_e32 v78, v8, v8
	v_fmac_f32_e32 v79, v10, v10
	v_add_f32_e32 v78, v78, v79
	v_add_f32_e32 v77, v78, v77
	v_mov_b32_e32 v78, v76
	v_mov_b32_e32 v79, v77
	s_nop 0
	v_permlane16_swap_b32_e32 v76, v78
	v_permlane16_swap_b32_e32 v77, v79
	v_add_f32_e32 v76, v76, v78
	v_add_f32_e32 v77, v77, v79
	v_mov_b32_e32 v78, v76
	v_mov_b32_e32 v79, v77
	s_nop 0
	v_permlane32_swap_b32_e32 v76, v78
	v_permlane32_swap_b32_e32 v77, v79
	s_and_saveexec_b64 s[6:7], s[8:9]
	v_pk_add_f32 v[76:77], v[76:77], v[78:79]
	ds_write_b64 v190, v[76:77] offset:5632
	s_or_b64 exec, exec, s[6:7]
	s_waitcnt lgkmcnt(0)
	s_barrier
	s_add_u32 s56, s26, 0x1ac00000
	v_add_u32_e32 v156, s68, v186
	s_addc_u32 s57, s27, 0
	v_ashrrev_i32_e32 v157, 31, v156
	s_and_saveexec_b64 s[6:7], s[10:11]
	s_cbranch_execz .LBB0_835
	ds_read_b128 v[76:79], v189
	ds_read_b128 v[88:91], v189 offset:16
	s_ashr_i32 s83, s82, 31
	s_waitcnt lgkmcnt(1)
	v_mov_b32_e32 v92, v76
	s_waitcnt lgkmcnt(0)
	v_mov_b32_e32 v93, v88
	v_mov_b32_e32 v94, v78
	v_mov_b32_e32 v95, v90
	v_pk_add_f32 v[92:93], v[92:93], v[94:95]
	v_mov_b32_e32 v88, v77
	v_mov_b32_e32 v90, v79
	v_add_f32_e32 v78, v92, v93
	v_pk_add_f32 v[76:77], v[88:89], v[90:91]
	s_nop 0
	v_add_f32_e32 v77, v76, v77
	v_mul_f32_e32 v76, 0x3b800000, v78
	v_fma_f32 v77, -v78, v76, v77
	v_lshlrev_b64 v[78:79], 6, v[156:157]
	v_lshl_add_u64 v[78:79], s[56:57], 0, v[78:79]
	v_max_f32_e32 v77, 0, v77
	v_lshl_add_u64 v[78:79], s[82:83], 3, v[78:79]
	global_store_dwordx2 v[78:79], v[76:77], off sc1
